# GEMM prologues issue all 14 stage loads before the first wait; attention Q loads issued with first K/V tile; conv unit first token loads issued with halo/weight loads
# baseline (speedup 1.0000x reference)
; #define PG8_STAGE(bufoff, gbase, voff) do { _Pragma("unroll") for (int _i = 0; _i < 2; ++_i) \
;         __builtin_amdgcn_global_load_lds((const unsigned*)((const char*)(gbase) + (voff)[_i]), (LAS unsigned*)(lds + (bufoff) + ldsw + _i * 8192), 16, 0, 0); } while (0)
; #define PG8_WAIT_V(n) asm volatile("s_waitcnt vmcnt(" #n ")" ::: "memory")
; #define PG8_BAR __builtin_amdgcn_s_barrier()
; template <class Epi, class Sched, bool ALIGN_EPI, bool I8 = false>
; __device__ __forceinline__ void gemm_phase(LAS unsigned char* lds, const Gemm g, const Sched& S, const Epi& E) {
;     ...
;     PG8_STAGE(PG8_SB(0, 0), cB, voffB); PG8_STAGE(PG8_SB(0, 1), cB + hstep, voffB); PG8_STAGE(PG8_SA(0, 0), cA, voffA); PG8_STAGE(PG8_SA(0, 1), cA + hstep, voffA);
;     if (wr == 1) PG8_BAR;
;     PG8_WAIT_V(2); PG8_BAR;
;     PG8_STAGE(PG8_SB(1, 0), cB + kstep, voffB); PG8_STAGE(PG8_SA(1, 0), cA + kstep, voffA); PG8_STAGE(PG8_SB(1, 1), cB + hstep + kstep, voffB);
;     PG8_WAIT_V(6); PG8_BAR;
.LBB0_109:
	s_add_u32 s10, s20, 0x37400000
	s_addc_u32 s11, s21, 0
	s_lshl_b32 s5, s12, 5
	s_mov_b64 s[12:13], 0x80
	s_add_i32 m0, s54, 0x18000
	v_lshl_add_u64 v[6:7], v[6:7], 0, s[12:13]
	s_lshl_b32 s4, s3, 13
	s_and_b32 s5, s5, 0x60
	global_load_lds_dwordx4 v[6:7], off
	v_lshl_add_u64 v[4:5], v[4:5], 0, s[12:13]
	s_add_i32 m0, s54, 0x1a000
	s_add_i32 s60, s54, 0x8000
	s_add_i32 s61, s54, 0xa000
	global_load_lds_dwordx4 v[4:5], off
	v_lshl_add_u64 v[0:1], v[0:1], 0, s[12:13]
	s_mov_b32 m0, s60
	s_add_u32 s16, s44, 0x80080
	global_load_lds_dwordx4 v[0:1], off
	v_lshl_add_u64 v[0:1], v[2:3], 0, s[12:13]
	s_mov_b32 m0, s61
	s_addc_u32 s17, s45, 0
	global_load_lds_dwordx4 v[0:1], off
	s_add_i32 m0, s54, 0x1c000
	v_lshl_add_u64 v[0:1], s[16:17], 0, v[130:131]
	global_load_lds_dwordx4 v[0:1], off
	v_lshl_add_u64 v[0:1], s[16:17], 0, v[134:135]
	s_add_i32 m0, s54, 0x1e000
	v_lshlrev_b32_e32 v2, 12, v156
	global_load_lds_dwordx4 v[0:1], off
	v_lshlrev_b32_e32 v1, 2, v154
	v_lshl_or_b32 v0, v154, 6, v155
	v_and_b32_e32 v1, 32, v1
	v_bitop3_b32 v0, v0, s4, v1 bitop3:0xde
	v_lshlrev_b32_e32 v1, 9, v217
	v_and_b32_e32 v1, 0x70000, v1
	v_or3_b32 v1, v158, v1, v2
	v_add_u32_e32 v138, v1, v159
	v_lshlrev_b32_e32 v1, 5, v160
	s_waitcnt vmcnt(8)
	s_barrier
	s_waitcnt vmcnt(6)
	s_cmpk_lt_u32 s14, 0x100
	v_and_b32_e32 v1, 0xf0000, v1
	v_lshl_or_b32 v166, s5, 7, v157
	s_cselect_b64 s[14:15], -1, 0
	v_or3_b32 v1, v158, v1, v2
	s_add_i32 s65, 0, 0x10000
	s_add_i32 s66, 0, 0x14000
	s_sext_i32_i16 s83, s2
	v_lshl_or_b32 v165, s3, 6, v154
	s_mov_b32 s62, 0x18000
	s_mov_b32 s63, 0x8000
	s_ashr_i32 s64, s6, 31
	v_or_b32_e32 v167, s5, v152
	v_mov_b32_e32 v139, v137
	v_add_u32_e32 v140, v1, v159
	v_mov_b32_e32 v141, v137
	v_mov_b64_e32 v[142:143], 0x800
	v_mov_b64_e32 v[144:145], 0x7ff
	v_add_u32_e32 v168, s65, v166
	v_add_u32_e32 v169, s66, v166
	v_add_u32_e32 v170, 0, v0
	s_mov_b64 s[16:17], 0x40000
	s_mov_b32 s67, 0x40000
	s_mov_b64 s[18:19], 0x48000
	s_mov_b32 s68, 0x48000
	s_mov_b64 s[24:25], 0x50000
	s_mov_b32 s69, 0x50000
	s_mov_b64 s[26:27], 0x58000
	s_mov_b32 s70, 0x58000
	s_mov_b32 s71, 0x20000
	s_mov_b32 s72, 0x28000
	s_mov_b32 s73, 0x30000
	s_mov_b32 s74, 0x38000
	s_mov_b32 s75, 0x404000
	s_mov_b32 s76, 0x40c000
	s_mov_b32 s77, 0x414000
	s_mov_b32 s78, 0x41c000
	s_mov_b32 s79, 0x424000
	s_mov_b32 s80, 0x42c000
	s_mov_b32 s81, 0x434000
	s_mov_b32 s82, 0x43c000
	s_mov_b32 s28, 0xbfb8aa3b
	v_mov_b32_e32 v171, 0x3e38aa3b
	s_barrier
	s_branch .LBB0_112

; #define PG8_STAGE(bufoff, gbase, voff) do { _Pragma("unroll") for (int _i = 0; _i < 2; ++_i) \
;         __builtin_amdgcn_global_load_lds((const unsigned*)((const char*)(gbase) + (voff)[_i]), (LAS unsigned*)(lds + (bufoff) + ldsw + _i * 8192), 16, 0, 0); } while (0)
; #define PG8_WAIT_V(n) asm volatile("s_waitcnt vmcnt(" #n ")" ::: "memory")
; #define PG8_BAR __builtin_amdgcn_s_barrier()
; template <class Epi, class Sched, bool ALIGN_EPI, bool I8 = false>
; __device__ __forceinline__ void gemm_phase(LAS unsigned char* lds, const Gemm g, const Sched& S, const Epi& E) {
;     ...
;     PG8_STAGE(PG8_SB(0, 0), cB, voffB); PG8_STAGE(PG8_SB(0, 1), cB + hstep, voffB); PG8_STAGE(PG8_SA(0, 0), cA, voffA); PG8_STAGE(PG8_SA(0, 1), cA + hstep, voffA);
;     if (wr == 1) PG8_BAR;
;     PG8_WAIT_V(2); PG8_BAR;
;     PG8_STAGE(PG8_SB(1, 0), cB + kstep, voffB); PG8_STAGE(PG8_SA(1, 0), cA + kstep, voffA); PG8_STAGE(PG8_SB(1, 1), cB + hstep + kstep, voffB);
;     PG8_WAIT_V(6); PG8_BAR;
.LBB0_137:
	s_add_u32 s12, s20, 0x3fc00000
	s_addc_u32 s13, s21, 0
	s_lshl_b32 s5, s14, 5
	s_lshl_b32 s4, s24, 13
	s_and_b32 s5, s5, 0x60
	s_add_u32 s14, s20, 0x25200000
	s_addc_u32 s15, s21, 0
	s_add_u32 s16, s20, 0x39600000
	s_mov_b64 s[18:19], 0x80
	s_addc_u32 s17, s21, 0
	s_add_i32 m0, s67, 0x18000
	v_lshl_add_u64 v[6:7], v[6:7], 0, s[18:19]
	global_load_lds_dwordx4 v[6:7], off
	v_lshl_add_u64 v[4:5], v[4:5], 0, s[18:19]
	s_add_i32 m0, s67, 0x1a000
	s_add_i32 s73, s67, 0x8000
	s_add_i32 s74, s67, 0xa000
	global_load_lds_dwordx4 v[4:5], off
	v_lshl_add_u64 v[0:1], v[0:1], 0, s[18:19]
	s_mov_b32 m0, s73
	s_add_u32 s30, s56, 0x40080
	global_load_lds_dwordx4 v[0:1], off
	v_lshl_add_u64 v[0:1], v[2:3], 0, s[18:19]
	s_mov_b32 m0, s74
	s_addc_u32 s31, s57, 0
	global_load_lds_dwordx4 v[0:1], off
	s_add_i32 m0, s67, 0x1c000
	v_lshl_add_u64 v[0:1], s[30:31], 0, v[148:149]
	global_load_lds_dwordx4 v[0:1], off
	v_lshl_add_u64 v[0:1], s[30:31], 0, v[144:145]
	s_add_i32 m0, s67, 0x1e000
	v_or_b32_e32 v223, s5, v152
	global_load_lds_dwordx4 v[0:1], off
	v_lshlrev_b32_e32 v1, 2, v154
	v_lshl_or_b32 v0, v154, 6, v155
	v_and_b32_e32 v1, 32, v1
	v_lshlrev_b32_e32 v152, 2, v223
	s_sext_i32_i16 s60, s2
	v_bitop3_b32 v2, v0, s4, v1 bitop3:0xde
	s_cmpk_lt_u32 s3, 0x100
	v_lshl_add_u64 v[0:1], s[20:21], 0, v[152:153]
	s_mov_b64 s[2:3], 0x4000
	v_lshl_or_b32 v219, s24, 6, v154
	v_lshl_add_u64 v[154:155], v[0:1], 0, s[2:3]
	v_lshlrev_b32_e32 v0, 8, v217
	v_and_b32_e32 v0, 0x38000, v0
	v_lshlrev_b32_e32 v1, 11, v156
	v_or3_b32 v0, v158, v0, v1
	v_add_u32_e32 v156, v0, v159
	v_lshlrev_b32_e32 v0, 4, v160
	s_waitcnt vmcnt(8)
	s_barrier
	s_waitcnt vmcnt(6)
	v_and_b32_e32 v0, 0x78000, v0
	v_lshl_or_b32 v222, s5, 7, v157
	s_cselect_b64 s[24:25], -1, 0
	v_or3_b32 v0, v158, v0, v1
	s_add_i32 s79, 0, 0x10000
	s_add_i32 s80, 0, 0x14000
	s_mov_b32 s75, 0x18000
	s_mov_b32 s76, 0x8000
	v_or_b32_e32 v224, 0xfffff400, v223
	s_ashr_i32 s77, s6, 31
	s_mov_b32 s78, 0x38000
	v_mov_b32_e32 v157, v153
	v_add_u32_e32 v158, v0, v159
	v_mov_b32_e32 v159, v153
	v_mov_b64_e32 v[160:161], 0x900
	v_mov_b64_e32 v[162:163], 0x8ff
	v_add_u32_e32 v225, s79, v222
	v_add_u32_e32 v226, s80, v222
	v_add_u32_e32 v227, 0, v2
	s_mov_b32 s26, 0x3c010204
	s_mov_b32 s28, 0xbfb8aa3b
	s_mov_b32 s81, 0x40000
	s_mov_b64 s[30:31], 0x48000
	s_mov_b32 s82, 0x48000
	s_mov_b64 s[34:35], 0x50000
	s_mov_b32 s83, 0x50000
	s_mov_b64 s[36:37], 0x58000
	s_mov_b32 s84, 0x58000
	s_mov_b32 s38, 0x3dd2d3e9
	s_mov_b32 s40, 0xc0135761
	s_mov_b32 s86, 0x20000
	s_mov_b32 s87, 0x28000
	s_mov_b32 s88, 0x30000
	s_mov_b32 s89, 0x404000
	s_mov_b32 s90, 0x40c000
	s_mov_b32 s91, 0x414000
	s_mov_b32 s92, 0x41c000
	s_mov_b32 s93, 0x424000
	s_mov_b32 s94, 0x42c000
	s_mov_b32 s95, 0x434000
	s_mov_b32 s96, 0x43c000
	s_mov_b32 s42, 0xbc3a1e78
	s_movk_i32 s97, 0x3000
	s_barrier
	s_branch .LBB0_140

; __device__ __forceinline__ void unpack8(const u32x4 w, float* v) { v[0] = bflo(w.x); v[1] = bfhi(w.x); v[2] = bflo(w.y); v[3] = bfhi(w.y); v[4] = bflo(w.z); v[5] = bfhi(w.z); v[6] = bflo(w.w); v[7] = bfhi(w.w); }
; __device__ __forceinline__ void conv_unit(const bf16_t* __restrict__ BB, const bf16_t* __restrict__ CC, const bf16_t* __restrict__ HB, const bf16_t* __restrict__ GB,
;                                           bf16_t* __restrict__ OB, const float* __restrict__ cw, int unit, int tid) {
;     const int cgp = tid & 127, sub = tid >> 7, ch = cgp * 8;
;     const int t0 = unit * 32 + sub * 8;
;     float w0[8], w1[8], w2[8];
; #pragma unroll
;     for (int e = 0; e < 8; ++e) { w0[e] = cw[ch + e]; w1[e] = cw[DH + ch + e]; w2[e] = cw[2 * DH + ch + e]; }
;     float p2[8], p1[8];
; #pragma unroll
;     for (int e = 0; e < 8; ++e) { p2[e] = 0.f; p1[e] = 0.f; }
;     const int tpos = t0 & (SEQ - 1);
;     if (tpos >= 2) { float a[8], b[8]; unpack8(*(const u32x4*)(CC + (size_t)(t0 - 2) * DH + ch), a); unpack8(*(const u32x4*)(HB + (size_t)(t0 - 2) * DH + ch), b);
; #pragma unroll
;         for (int e = 0; e < 8; ++e) p2[e] = a[e] * b[e]; }
;     if (tpos >= 1) { float a[8], b[8]; unpack8(*(const u32x4*)(CC + (size_t)(t0 - 1) * DH + ch), a); unpack8(*(const u32x4*)(HB + (size_t)(t0 - 1) * DH + ch), b);
; #pragma unroll
;         for (int e = 0; e < 8; ++e) p1[e] = a[e] * b[e]; }
; #pragma unroll
;     for (int i = 0; i < 8; ++i) {
;         const size_t off = (size_t)(t0 + i) * DH + ch;
;         float a[8], b[8], g1[8], g2[8], o[8];
;         unpack8(*(const u32x4*)(CC + off), a); unpack8(*(const u32x4*)(HB + off), b); unpack8(*(const u32x4*)(BB + off), g1); unpack8(*(const u32x4*)(GB + off), g2);
; #pragma unroll
;         for (int e = 0; e < 8; ++e) { const float cur = a[e] * b[e]; o[e] = g1[e] * (w0[e] * p2[e] + w1[e] * p1[e] + w2[e] * cur) * g2[e]; p2[e] = p1[e]; p1[e] = cur; }
.LBB0_235:
	s_and_b64 vcc, exec, s[8:9]
	s_cbranch_vccz .LBB0_246
	global_load_dwordx4 v[0:3], v[140:141], off offset:16
	global_load_dwordx4 v[12:15], v[140:141], off
	global_load_dwordx4 v[4:7], v[142:143], off offset:16
	global_load_dwordx4 v[20:23], v[142:143], off
	global_load_dwordx4 v[8:11], v[144:145], off offset:16
	global_load_dwordx4 v[16:19], v[144:145], off
	v_lshl_add_u32 v32, s84, 5, v161
	v_lshlrev_b32_e32 v56, 10, v32
	v_or_b32_e32 v57, v56, v160
	v_lshlrev_b32_e32 v57, 1, v57
	global_load_dwordx4 v[48:51], v57, s[40:41]
	global_load_dwordx4 v[52:55], v57, s[42:43]
	global_load_dwordx4 v[58:61], v57, s[38:39]
	global_load_dwordx4 v[62:65], v57, s[44:45]
	v_or_b32_e32 v108, 0x800, v57
	global_load_dwordx4 v[66:69], v108, s[40:41]
	global_load_dwordx4 v[70:73], v108, s[42:43]
	global_load_dwordx4 v[74:77], v108, s[38:39]
	global_load_dwordx4 v[78:81], v108, s[44:45]
	v_and_b32_e32 v24, 0x7f8, v32
	v_cmp_ne_u32_e32 vcc, 0, v24
	v_mov_b32_e32 v46, 0
	v_mov_b32_e32 v47, 0
	v_mov_b32_e32 v44, 0
	v_mov_b32_e32 v45, 0
	v_mov_b32_e32 v42, 0
	v_mov_b32_e32 v43, 0
	v_mov_b32_e32 v40, 0
	v_mov_b32_e32 v41, 0
	v_mov_b32_e32 v24, 0
	v_mov_b32_e32 v25, 0
	v_mov_b32_e32 v26, 0
	v_mov_b32_e32 v27, 0
	v_mov_b32_e32 v28, 0
	v_mov_b32_e32 v29, 0
	v_mov_b32_e32 v30, 0
	v_mov_b32_e32 v31, 0
	s_and_saveexec_b64 s[8:9], vcc
	s_cbranch_execz .LBB0_238
	v_add_u32_e32 v132, -2, v32
	v_lshlrev_b64 v[28:29], 11, v[132:133]
	v_add_u32_e32 v132, -1, v32
	v_lshl_add_u64 v[24:25], v[134:135], 0, v[28:29]
	v_lshl_add_u64 v[28:29], v[136:137], 0, v[28:29]
	v_lshlrev_b64 v[38:39], 11, v[132:133]
	global_load_dwordx4 v[24:27], v[24:25], off
	v_lshl_add_u64 v[34:35], v[134:135], 0, v[38:39]
	global_load_dwordx4 v[28:31], v[28:29], off
	v_lshl_add_u64 v[38:39], v[136:137], 0, v[38:39]
	global_load_dwordx4 v[34:37], v[34:35], off
	global_load_dwordx4 v[38:41], v[38:39], off
	s_waitcnt vmcnt(0)
	v_lshlrev_b32_e32 v42, 16, v24
	v_and_b32_e32 v43, 0xffff0000, v24
	v_lshlrev_b32_e32 v44, 16, v28
	v_and_b32_e32 v45, 0xffff0000, v28
	v_lshlrev_b32_e32 v46, 16, v25
	v_and_b32_e32 v47, 0xffff0000, v25
	v_lshlrev_b32_e32 v28, 16, v29
	v_and_b32_e32 v29, 0xffff0000, v29
	v_lshlrev_b32_e32 v236, 16, v26
	v_and_b32_e32 v237, 0xffff0000, v26
	v_lshlrev_b32_e32 v238, 16, v30
	v_and_b32_e32 v239, 0xffff0000, v30
	v_lshlrev_b32_e32 v240, 16, v27
	v_and_b32_e32 v241, 0xffff0000, v27
	v_lshlrev_b32_e32 v30, 16, v31
	v_and_b32_e32 v31, 0xffff0000, v31
	v_pk_mul_f32 v[24:25], v[42:43], v[44:45]
	v_pk_mul_f32 v[26:27], v[46:47], v[28:29]
	v_pk_mul_f32 v[28:29], v[236:237], v[238:239]
	v_lshlrev_b32_e32 v42, 16, v34
	v_and_b32_e32 v43, 0xffff0000, v34
	v_lshlrev_b32_e32 v34, 16, v35
	v_and_b32_e32 v35, 0xffff0000, v35
	v_lshlrev_b32_e32 v236, 16, v36
	v_and_b32_e32 v237, 0xffff0000, v36
	v_lshlrev_b32_e32 v36, 16, v37
	v_and_b32_e32 v37, 0xffff0000, v37
	v_pk_mul_f32 v[30:31], v[240:241], v[30:31]
	s_waitcnt vmcnt(0)
	v_lshlrev_b32_e32 v44, 16, v38
	v_and_b32_e32 v45, 0xffff0000, v38
	v_lshlrev_b32_e32 v38, 16, v39
	v_and_b32_e32 v39, 0xffff0000, v39
	v_lshlrev_b32_e32 v238, 16, v40
	v_and_b32_e32 v239, 0xffff0000, v40
	v_lshlrev_b32_e32 v40, 16, v41
	v_and_b32_e32 v41, 0xffff0000, v41
	v_pk_mul_f32 v[46:47], v[42:43], v[44:45]
	v_pk_mul_f32 v[44:45], v[34:35], v[38:39]
	v_pk_mul_f32 v[42:43], v[236:237], v[238:239]
	v_pk_mul_f32 v[40:41], v[36:37], v[40:41]
.LBB0_238:
	s_or_b64 exec, exec, s[8:9]
	v_lshlrev_b32_e32 v56, 10, v32
	v_or_b32_e32 v32, v56, v160
	v_lshlrev_b32_e32 v57, 1, v32
	v_or_b32_e32 v108, 0x800, v57
	s_waitcnt vmcnt(0)
	v_pk_mul_f32 v[24:25], v[12:13], v[24:25]
	v_pk_mul_f32 v[26:27], v[14:15], v[26:27]
	v_pk_mul_f32 v[28:29], v[0:1], v[28:29]
	v_pk_mul_f32 v[30:31], v[2:3], v[30:31]
	v_or_b32_e32 v109, 0x1000, v57
	v_pk_fma_f32 v[82:83], v[20:21], v[46:47], v[24:25]
	v_pk_fma_f32 v[84:85], v[22:23], v[44:45], v[26:27]
	v_pk_fma_f32 v[86:87], v[4:5], v[42:43], v[28:29]
	v_pk_fma_f32 v[88:89], v[6:7], v[40:41], v[30:31]
	global_load_dwordx4 v[32:35], v109, s[40:41]
	global_load_dwordx4 v[24:27], v109, s[38:39]
	global_load_dwordx4 v[36:39], v109, s[42:43]
	global_load_dwordx4 v[28:31], v109, s[44:45]
	s_mov_b64 s[8:9], 0
	v_lshlrev_b32_e32 v90, 16, v48
	v_and_b32_e32 v91, 0xffff0000, v48
	v_lshlrev_b32_e32 v92, 16, v52
	v_and_b32_e32 v93, 0xffff0000, v52
	v_lshlrev_b32_e32 v48, 16, v49
	v_and_b32_e32 v49, 0xffff0000, v49
	v_lshlrev_b32_e32 v52, 16, v53
	v_and_b32_e32 v53, 0xffff0000, v53
	v_lshlrev_b32_e32 v98, 16, v50
	v_and_b32_e32 v99, 0xffff0000, v50
	v_lshlrev_b32_e32 v100, 16, v54
	v_and_b32_e32 v101, 0xffff0000, v54
	v_lshlrev_b32_e32 v50, 16, v51
	v_and_b32_e32 v51, 0xffff0000, v51
	v_lshlrev_b32_e32 v54, 16, v55
	v_and_b32_e32 v55, 0xffff0000, v55
	v_pk_mul_f32 v[90:91], v[90:91], v[92:93]
	v_pk_mul_f32 v[92:93], v[48:49], v[52:53]
	v_pk_mul_f32 v[98:99], v[98:99], v[100:101]
	v_pk_mul_f32 v[50:51], v[50:51], v[54:55]
	v_lshlrev_b32_e32 v48, 16, v66
	v_and_b32_e32 v49, 0xffff0000, v66
	v_lshlrev_b32_e32 v52, 16, v70
	v_and_b32_e32 v53, 0xffff0000, v70
	v_lshlrev_b32_e32 v94, 16, v58
	v_and_b32_e32 v95, 0xffff0000, v58
	v_lshlrev_b32_e32 v58, 16, v59
	v_and_b32_e32 v59, 0xffff0000, v59
	v_lshlrev_b32_e32 v102, 16, v60
	v_and_b32_e32 v103, 0xffff0000, v60
	v_lshlrev_b32_e32 v60, 16, v61
	v_and_b32_e32 v61, 0xffff0000, v61
	v_pk_fma_f32 v[54:55], v[16:17], v[90:91], v[82:83]
	v_pk_fma_f32 v[82:83], v[18:19], v[92:93], v[84:85]
	v_pk_fma_f32 v[84:85], v[8:9], v[98:99], v[86:87]
	v_pk_fma_f32 v[86:87], v[10:11], v[50:51], v[88:89]
	v_pk_mul_f32 v[48:49], v[48:49], v[52:53]
	v_pk_mul_f32 v[52:53], v[20:21], v[90:91]
	v_lshlrev_b32_e32 v96, 16, v62
; __device__ __forceinline__ unsigned pk2(float lo, float hi) { f32x2 v = {lo, hi}; bf16x2_t b = __builtin_convertvector(v, bf16x2_t); return __builtin_bit_cast(unsigned, b); }
; __device__ __forceinline__ void unpack8(const u32x4 w, float* v) { v[0] = bflo(w.x); v[1] = bfhi(w.x); v[2] = bflo(w.y); v[3] = bfhi(w.y); v[4] = bflo(w.z); v[5] = bfhi(w.z); v[6] = bflo(w.w); v[7] = bfhi(w.w); }
; __device__ __forceinline__ void conv_unit(const bf16_t* __restrict__ BB, const bf16_t* __restrict__ CC, const bf16_t* __restrict__ HB, const bf16_t* __restrict__ GB,
;                                           bf16_t* __restrict__ OB, const float* __restrict__ cw, int unit, int tid) {
;     ...
; #pragma unroll
;     for (int i = 0; i < 8; ++i) {
;         const size_t off = (size_t)(t0 + i) * DH + ch;
;         float a[8], b[8], g1[8], g2[8], o[8];
;         unpack8(*(const u32x4*)(CC + off), a); unpack8(*(const u32x4*)(HB + off), b); unpack8(*(const u32x4*)(BB + off), g1); unpack8(*(const u32x4*)(GB + off), g2);
; #pragma unroll
;         for (int e = 0; e < 8; ++e) { const float cur = a[e] * b[e]; o[e] = g1[e] * (w0[e] * p2[e] + w1[e] * p1[e] + w2[e] * cur) * g2[e]; p2[e] = p1[e]; p1[e] = cur; }
;         u32x4 w; w.x = pk2(o[0], o[1]); w.y = pk2(o[2], o[3]); w.z = pk2(o[4], o[5]); w.w = pk2(o[6], o[7]);
;         *(u32x4*)(OB + off) = w;
;     }
	v_and_b32_e32 v97, 0xffff0000, v62
	v_lshlrev_b32_e32 v62, 16, v63
	v_and_b32_e32 v63, 0xffff0000, v63
	v_lshlrev_b32_e32 v104, 16, v64
	v_and_b32_e32 v105, 0xffff0000, v64
	v_lshlrev_b32_e32 v64, 16, v65
	v_and_b32_e32 v65, 0xffff0000, v65
	v_pk_mul_f32 v[54:55], v[54:55], v[94:95]
	v_pk_mul_f32 v[58:59], v[82:83], v[58:59]
	v_pk_mul_f32 v[82:83], v[84:85], v[102:103]
	v_pk_mul_f32 v[60:61], v[86:87], v[60:61]
	v_pk_fma_f32 v[46:47], v[12:13], v[46:47], v[52:53]
	v_lshlrev_b32_e32 v100, 16, v74
	v_and_b32_e32 v101, 0xffff0000, v74
	v_pk_mul_f32 v[52:53], v[54:55], v[96:97]
	v_pk_mul_f32 v[54:55], v[58:59], v[62:63]
	v_pk_mul_f32 v[58:59], v[82:83], v[104:105]
	v_pk_mul_f32 v[60:61], v[60:61], v[64:65]
	v_pk_fma_f32 v[46:47], v[16:17], v[48:49], v[46:47]
	v_lshlrev_b32_e32 v106, 16, v78
	v_and_b32_e32 v107, 0xffff0000, v78
	v_cvt_pk_bf16_f32 v52, v52, v53
	v_cvt_pk_bf16_f32 v53, v54, v55
	v_cvt_pk_bf16_f32 v54, v58, v59
	v_cvt_pk_bf16_f32 v55, v60, v61
	v_pk_mul_f32 v[46:47], v[46:47], v[100:101]
	global_store_dwordx4 v57, v[52:55], s[46:47]
	v_lshlrev_b32_e32 v58, 16, v75
	v_and_b32_e32 v59, 0xffff0000, v75
	v_pk_mul_f32 v[52:53], v[46:47], v[106:107]
	v_lshlrev_b32_e32 v46, 16, v67
	v_and_b32_e32 v47, 0xffff0000, v67
	v_lshlrev_b32_e32 v54, 16, v71
	v_and_b32_e32 v55, 0xffff0000, v71
	v_pk_mul_f32 v[46:47], v[46:47], v[54:55]
	v_pk_mul_f32 v[54:55], v[22:23], v[92:93]
	v_lshlrev_b32_e32 v60, 16, v79
	v_pk_fma_f32 v[44:45], v[14:15], v[44:45], v[54:55]
	v_and_b32_e32 v61, 0xffff0000, v79
	v_pk_fma_f32 v[44:45], v[18:19], v[46:47], v[44:45]
	v_lshlrev_b32_e32 v62, 16, v80
	v_pk_mul_f32 v[44:45], v[44:45], v[58:59]
	v_lshlrev_b32_e32 v58, 16, v72
	v_pk_mul_f32 v[54:55], v[44:45], v[60:61]
	v_lshlrev_b32_e32 v44, 16, v68
	v_and_b32_e32 v45, 0xffff0000, v68
	v_and_b32_e32 v59, 0xffff0000, v72
	v_pk_mul_f32 v[44:45], v[44:45], v[58:59]
	v_pk_mul_f32 v[58:59], v[4:5], v[98:99]
	v_lshlrev_b32_e32 v60, 16, v76
	v_pk_fma_f32 v[42:43], v[0:1], v[42:43], v[58:59]
	v_and_b32_e32 v61, 0xffff0000, v76
	v_pk_fma_f32 v[42:43], v[8:9], v[44:45], v[42:43]
	v_and_b32_e32 v63, 0xffff0000, v80
	v_pk_mul_f32 v[42:43], v[42:43], v[60:61]
	v_lshlrev_b32_e32 v58, 16, v73
	v_pk_mul_f32 v[74:75], v[42:43], v[62:63]
	v_lshlrev_b32_e32 v42, 16, v69
	v_and_b32_e32 v43, 0xffff0000, v69
	v_and_b32_e32 v59, 0xffff0000, v73
	v_or_b32_e32 v94, 0x1800, v57
	v_pk_mul_f32 v[42:43], v[42:43], v[58:59]
	global_load_dwordx4 v[58:61], v94, s[40:41]
	global_load_dwordx4 v[62:65], v94, s[42:43]
	global_load_dwordx4 v[70:73], v94, s[44:45]
	v_pk_mul_f32 v[66:67], v[6:7], v[50:51]
	v_lshlrev_b32_e32 v76, 16, v77
	v_pk_fma_f32 v[40:41], v[2:3], v[40:41], v[66:67]
	global_load_dwordx4 v[66:69], v94, s[38:39]
	v_and_b32_e32 v77, 0xffff0000, v77
	v_pk_fma_f32 v[40:41], v[10:11], v[42:43], v[40:41]
	v_lshlrev_b32_e32 v78, 16, v81
	v_and_b32_e32 v79, 0xffff0000, v81
	v_pk_mul_f32 v[40:41], v[40:41], v[76:77]
	v_cvt_pk_bf16_f32 v52, v52, v53
	v_pk_mul_f32 v[40:41], v[40:41], v[78:79]
	v_cvt_pk_bf16_f32 v53, v54, v55
	v_cvt_pk_bf16_f32 v54, v74, v75
	v_cvt_pk_bf16_f32 v55, v40, v41
	global_store_dwordx4 v108, v[52:55], s[46:47]
	s_waitcnt vmcnt(9)
	v_lshlrev_b32_e32 v40, 16, v32
	v_and_b32_e32 v41, 0xffff0000, v32
	s_waitcnt vmcnt(7)
	v_lshlrev_b32_e32 v52, 16, v36
	v_and_b32_e32 v53, 0xffff0000, v36
	v_pk_mul_f32 v[40:41], v[40:41], v[52:53]
	v_pk_mul_f32 v[52:53], v[20:21], v[48:49]
	v_lshlrev_b32_e32 v54, 16, v24
	v_pk_fma_f32 v[52:53], v[12:13], v[90:91], v[52:53]
	v_and_b32_e32 v55, 0xffff0000, v24
	v_pk_fma_f32 v[52:53], v[16:17], v[40:41], v[52:53]
	s_waitcnt vmcnt(6)
	v_lshlrev_b32_e32 v74, 16, v28
	v_and_b32_e32 v75, 0xffff0000, v28
	v_pk_mul_f32 v[52:53], v[52:53], v[54:55]
	v_lshlrev_b32_e32 v32, 16, v33
	v_and_b32_e32 v33, 0xffff0000, v33
	v_lshlrev_b32_e32 v36, 16, v37
	v_and_b32_e32 v37, 0xffff0000, v37
	v_pk_mul_f32 v[90:91], v[52:53], v[74:75]
	v_pk_mul_f32 v[52:53], v[32:33], v[36:37]
	v_pk_mul_f32 v[32:33], v[22:23], v[46:47]
	v_lshlrev_b32_e32 v24, 16, v25
	v_pk_fma_f32 v[32:33], v[14:15], v[92:93], v[32:33]
	v_and_b32_e32 v25, 0xffff0000, v25
	v_pk_fma_f32 v[32:33], v[18:19], v[52:53], v[32:33]
	v_lshlrev_b32_e32 v28, 16, v29
	v_and_b32_e32 v29, 0xffff0000, v29
	v_pk_mul_f32 v[24:25], v[32:33], v[24:25]
	v_lshlrev_b32_e32 v32, 16, v38
	v_pk_mul_f32 v[28:29], v[24:25], v[28:29]
	v_lshlrev_b32_e32 v24, 16, v34
	v_and_b32_e32 v25, 0xffff0000, v34
	v_and_b32_e32 v33, 0xffff0000, v38
	v_pk_mul_f32 v[54:55], v[24:25], v[32:33]
	v_pk_mul_f32 v[24:25], v[4:5], v[44:45]
	v_lshlrev_b32_e32 v36, 16, v26
	v_pk_fma_f32 v[24:25], v[0:1], v[98:99], v[24:25]
	v_and_b32_e32 v37, 0xffff0000, v26
	v_pk_fma_f32 v[24:25], v[8:9], v[54:55], v[24:25]
	v_lshlrev_b32_e32 v74, 16, v30
	v_and_b32_e32 v75, 0xffff0000, v30
	v_pk_mul_f32 v[24:25], v[24:25], v[36:37]
	v_lshlrev_b32_e32 v34, 16, v39
	v_pk_mul_f32 v[32:33], v[24:25], v[74:75]
	v_lshlrev_b32_e32 v24, 16, v35
	v_and_b32_e32 v25, 0xffff0000, v35
	v_and_b32_e32 v35, 0xffff0000, v39
	v_pk_mul_f32 v[34:35], v[24:25], v[34:35]
	v_or_b32_e32 v92, 0x2000, v57
	v_pk_mul_f32 v[24:25], v[6:7], v[42:43]
	global_load_dwordx4 v[74:77], v92, s[40:41]
	global_load_dwordx4 v[82:85], v92, s[38:39]
	global_load_dwordx4 v[78:81], v92, s[42:43]
	global_load_dwordx4 v[86:89], v92, s[44:45]
	v_pk_fma_f32 v[24:25], v[2:3], v[50:51], v[24:25]
	v_lshlrev_b32_e32 v26, 16, v27
	v_and_b32_e32 v27, 0xffff0000, v27
	v_pk_fma_f32 v[24:25], v[10:11], v[34:35], v[24:25]
	v_lshlrev_b32_e32 v30, 16, v31
	v_and_b32_e32 v31, 0xffff0000, v31
	v_pk_mul_f32 v[24:25], v[24:25], v[26:27]
	v_cvt_pk_bf16_f32 v26, v32, v33
	v_pk_mul_f32 v[30:31], v[24:25], v[30:31]
	v_cvt_pk_bf16_f32 v24, v90, v91
	v_cvt_pk_bf16_f32 v25, v28, v29
	v_cvt_pk_bf16_f32 v27, v30, v31
	global_store_dwordx4 v109, v[24:27], s[46:47]
	s_waitcnt vmcnt(7)
; __device__ __forceinline__ unsigned pk2(float lo, float hi) { f32x2 v = {lo, hi}; bf16x2_t b = __builtin_convertvector(v, bf16x2_t); return __builtin_bit_cast(unsigned, b); }
; __device__ __forceinline__ void unpack8(const u32x4 w, float* v) { v[0] = bflo(w.x); v[1] = bfhi(w.x); v[2] = bflo(w.y); v[3] = bfhi(w.y); v[4] = bflo(w.z); v[5] = bfhi(w.z); v[6] = bflo(w.w); v[7] = bfhi(w.w); }
; __device__ __forceinline__ void conv_unit(const bf16_t* __restrict__ BB, const bf16_t* __restrict__ CC, const bf16_t* __restrict__ HB, const bf16_t* __restrict__ GB,
;                                           bf16_t* __restrict__ OB, const float* __restrict__ cw, int unit, int tid) {
;     ...
; #pragma unroll
;     for (int i = 0; i < 8; ++i) {
;         const size_t off = (size_t)(t0 + i) * DH + ch;
;         float a[8], b[8], g1[8], g2[8], o[8];
;         unpack8(*(const u32x4*)(CC + off), a); unpack8(*(const u32x4*)(HB + off), b); unpack8(*(const u32x4*)(BB + off), g1); unpack8(*(const u32x4*)(GB + off), g2);
; #pragma unroll
;         for (int e = 0; e < 8; ++e) { const float cur = a[e] * b[e]; o[e] = g1[e] * (w0[e] * p2[e] + w1[e] * p1[e] + w2[e] * cur) * g2[e]; p2[e] = p1[e]; p1[e] = cur; }
;         u32x4 w; w.x = pk2(o[0], o[1]); w.y = pk2(o[2], o[3]); w.z = pk2(o[4], o[5]); w.w = pk2(o[6], o[7]);
;         *(u32x4*)(OB + off) = w;
;     }
	v_lshlrev_b32_e32 v30, 16, v70
	v_and_b32_e32 v31, 0xffff0000, v70
	v_lshlrev_b32_e32 v24, 16, v58
	v_and_b32_e32 v25, 0xffff0000, v58
	v_lshlrev_b32_e32 v26, 16, v62
	v_and_b32_e32 v27, 0xffff0000, v62
	v_pk_mul_f32 v[50:51], v[24:25], v[26:27]
	v_pk_mul_f32 v[24:25], v[20:21], v[40:41]
	s_waitcnt vmcnt(6)
	v_lshlrev_b32_e32 v28, 16, v66
	v_pk_fma_f32 v[24:25], v[12:13], v[48:49], v[24:25]
	v_and_b32_e32 v29, 0xffff0000, v66
	v_pk_fma_f32 v[24:25], v[16:17], v[50:51], v[24:25]
	v_lshlrev_b32_e32 v26, 16, v63
	v_pk_mul_f32 v[24:25], v[24:25], v[28:29]
	v_and_b32_e32 v27, 0xffff0000, v63
	v_pk_mul_f32 v[36:37], v[24:25], v[30:31]
	v_lshlrev_b32_e32 v24, 16, v59
	v_and_b32_e32 v25, 0xffff0000, v59
	v_pk_mul_f32 v[48:49], v[24:25], v[26:27]
	v_pk_mul_f32 v[24:25], v[22:23], v[52:53]
	v_lshlrev_b32_e32 v28, 16, v67
	v_pk_fma_f32 v[24:25], v[14:15], v[46:47], v[24:25]
	v_and_b32_e32 v29, 0xffff0000, v67
	v_pk_fma_f32 v[24:25], v[18:19], v[48:49], v[24:25]
	v_lshlrev_b32_e32 v30, 16, v71
	v_and_b32_e32 v31, 0xffff0000, v71
	v_pk_mul_f32 v[24:25], v[24:25], v[28:29]
	v_lshlrev_b32_e32 v26, 16, v64
	v_pk_mul_f32 v[38:39], v[24:25], v[30:31]
	v_lshlrev_b32_e32 v24, 16, v60
	v_and_b32_e32 v25, 0xffff0000, v60
	v_and_b32_e32 v27, 0xffff0000, v64
	v_pk_mul_f32 v[46:47], v[24:25], v[26:27]
	v_pk_mul_f32 v[24:25], v[4:5], v[54:55]
	v_lshlrev_b32_e32 v28, 16, v68
	v_pk_fma_f32 v[24:25], v[0:1], v[44:45], v[24:25]
	v_and_b32_e32 v29, 0xffff0000, v68
	v_pk_fma_f32 v[24:25], v[8:9], v[46:47], v[24:25]
	v_lshlrev_b32_e32 v30, 16, v72
	v_and_b32_e32 v31, 0xffff0000, v72
	v_pk_mul_f32 v[24:25], v[24:25], v[28:29]
	v_or_b32_e32 v90, 0x2800, v57
	v_pk_mul_f32 v[44:45], v[24:25], v[30:31]
	v_lshlrev_b32_e32 v24, 16, v61
	v_and_b32_e32 v25, 0xffff0000, v61
	v_lshlrev_b32_e32 v26, 16, v65
	v_and_b32_e32 v27, 0xffff0000, v65
	global_load_dwordx4 v[58:61], v90, s[40:41]
	global_load_dwordx4 v[28:31], v90, s[38:39]
	global_load_dwordx4 v[62:65], v90, s[42:43]
	v_pk_mul_f32 v[32:33], v[24:25], v[26:27]
	v_pk_mul_f32 v[24:25], v[6:7], v[34:35]
	v_lshlrev_b32_e32 v66, 16, v69
	v_pk_fma_f32 v[24:25], v[2:3], v[42:43], v[24:25]
	v_and_b32_e32 v67, 0xffff0000, v69
	v_pk_fma_f32 v[42:43], v[10:11], v[32:33], v[24:25]
	global_load_dwordx4 v[24:27], v90, s[44:45]
	v_lshlrev_b32_e32 v68, 16, v73
	v_and_b32_e32 v69, 0xffff0000, v73
	v_pk_mul_f32 v[42:43], v[42:43], v[66:67]
	v_cvt_pk_bf16_f32 v36, v36, v37
	v_pk_mul_f32 v[42:43], v[42:43], v[68:69]
	v_cvt_pk_bf16_f32 v37, v38, v39
	v_cvt_pk_bf16_f32 v38, v44, v45
	v_cvt_pk_bf16_f32 v39, v42, v43
	global_store_dwordx4 v94, v[36:39], s[46:47]
	s_waitcnt vmcnt(8)
	v_lshlrev_b32_e32 v42, 16, v82
	v_and_b32_e32 v43, 0xffff0000, v82
	v_lshlrev_b32_e32 v36, 16, v74
	v_and_b32_e32 v37, 0xffff0000, v74
	s_waitcnt vmcnt(7)
	v_lshlrev_b32_e32 v38, 16, v78
	v_and_b32_e32 v39, 0xffff0000, v78
	v_pk_mul_f32 v[36:37], v[36:37], v[38:39]
	v_pk_mul_f32 v[38:39], v[20:21], v[50:51]
	s_waitcnt vmcnt(6)
	v_lshlrev_b32_e32 v44, 16, v86
	v_pk_fma_f32 v[38:39], v[12:13], v[40:41], v[38:39]
	v_and_b32_e32 v45, 0xffff0000, v86
	v_pk_fma_f32 v[38:39], v[16:17], v[36:37], v[38:39]
	v_lshlrev_b32_e32 v40, 16, v79
	v_pk_mul_f32 v[38:39], v[38:39], v[42:43]
	v_and_b32_e32 v41, 0xffff0000, v79
	v_pk_mul_f32 v[44:45], v[38:39], v[44:45]
	v_lshlrev_b32_e32 v38, 16, v75
	v_and_b32_e32 v39, 0xffff0000, v75
	v_pk_mul_f32 v[38:39], v[38:39], v[40:41]
	v_pk_mul_f32 v[40:41], v[22:23], v[48:49]
	v_lshlrev_b32_e32 v42, 16, v83
	v_pk_fma_f32 v[40:41], v[14:15], v[52:53], v[40:41]
	v_and_b32_e32 v43, 0xffff0000, v83
	v_pk_fma_f32 v[40:41], v[18:19], v[38:39], v[40:41]
	v_lshlrev_b32_e32 v66, 16, v87
	v_and_b32_e32 v67, 0xffff0000, v87
	v_pk_mul_f32 v[40:41], v[40:41], v[42:43]
	v_lshlrev_b32_e32 v42, 16, v80
	v_pk_mul_f32 v[82:83], v[40:41], v[66:67]
	v_lshlrev_b32_e32 v40, 16, v76
	v_and_b32_e32 v41, 0xffff0000, v76
	v_and_b32_e32 v43, 0xffff0000, v80
	v_pk_mul_f32 v[40:41], v[40:41], v[42:43]
	v_pk_mul_f32 v[42:43], v[4:5], v[46:47]
	v_lshlrev_b32_e32 v52, 16, v84
	v_pk_fma_f32 v[42:43], v[0:1], v[54:55], v[42:43]
	v_and_b32_e32 v53, 0xffff0000, v84
	v_pk_fma_f32 v[42:43], v[8:9], v[40:41], v[42:43]
	v_lshlrev_b32_e32 v66, 16, v88
	v_and_b32_e32 v67, 0xffff0000, v88
	v_pk_mul_f32 v[42:43], v[42:43], v[52:53]
	v_lshlrev_b32_e32 v52, 16, v81
	v_pk_mul_f32 v[86:87], v[42:43], v[66:67]
	v_lshlrev_b32_e32 v42, 16, v77
	v_and_b32_e32 v43, 0xffff0000, v77
	v_and_b32_e32 v53, 0xffff0000, v81
	v_pk_mul_f32 v[66:67], v[6:7], v[32:33]
	v_or_b32_e32 v88, 0x3000, v57
	v_pk_mul_f32 v[42:43], v[42:43], v[52:53]
	global_load_dwordx4 v[52:55], v88, s[40:41]
	global_load_dwordx4 v[70:73], v88, s[38:39]
	v_pk_fma_f32 v[34:35], v[2:3], v[34:35], v[66:67]
	global_load_dwordx4 v[66:69], v88, s[42:43]
	v_lshlrev_b32_e32 v74, 16, v85
	v_and_b32_e32 v75, 0xffff0000, v85
	v_pk_fma_f32 v[34:35], v[10:11], v[42:43], v[34:35]
	v_lshlrev_b32_e32 v78, 16, v89
	v_and_b32_e32 v79, 0xffff0000, v89
	v_pk_mul_f32 v[34:35], v[34:35], v[74:75]
	v_cvt_pk_bf16_f32 v80, v86, v87
	v_pk_mul_f32 v[34:35], v[34:35], v[78:79]
	v_cvt_pk_bf16_f32 v78, v44, v45
	v_cvt_pk_bf16_f32 v81, v34, v35
	s_waitcnt vmcnt(7)
	v_lshlrev_b32_e32 v34, 16, v58
	v_and_b32_e32 v35, 0xffff0000, v58
	s_waitcnt vmcnt(5)
	v_lshlrev_b32_e32 v44, 16, v62
	v_and_b32_e32 v45, 0xffff0000, v62
	v_pk_mul_f32 v[34:35], v[34:35], v[44:45]
	v_pk_mul_f32 v[44:45], v[20:21], v[36:37]
	v_cvt_pk_bf16_f32 v79, v82, v83
	v_pk_fma_f32 v[44:45], v[12:13], v[50:51], v[44:45]
	global_store_dwordx4 v92, v[78:81], s[46:47]
	v_pk_fma_f32 v[44:45], v[16:17], v[34:35], v[44:45]
	v_lshlrev_b32_e32 v50, 16, v63
	v_lshlrev_b32_e32 v78, 16, v28
	v_and_b32_e32 v79, 0xffff0000, v28
	s_waitcnt vmcnt(5)
; __device__ __forceinline__ unsigned pk2(float lo, float hi) { f32x2 v = {lo, hi}; bf16x2_t b = __builtin_convertvector(v, bf16x2_t); return __builtin_bit_cast(unsigned, b); }
; __device__ __forceinline__ void unpack8(const u32x4 w, float* v) { v[0] = bflo(w.x); v[1] = bfhi(w.x); v[2] = bflo(w.y); v[3] = bfhi(w.y); v[4] = bflo(w.z); v[5] = bfhi(w.z); v[6] = bflo(w.w); v[7] = bfhi(w.w); }
; __device__ __forceinline__ void conv_unit(const bf16_t* __restrict__ BB, const bf16_t* __restrict__ CC, const bf16_t* __restrict__ HB, const bf16_t* __restrict__ GB,
;                                           bf16_t* __restrict__ OB, const float* __restrict__ cw, int unit, int tid) {
;     ...
; #pragma unroll
;     for (int i = 0; i < 8; ++i) {
;         const size_t off = (size_t)(t0 + i) * DH + ch;
;         float a[8], b[8], g1[8], g2[8], o[8];
;         unpack8(*(const u32x4*)(CC + off), a); unpack8(*(const u32x4*)(HB + off), b); unpack8(*(const u32x4*)(BB + off), g1); unpack8(*(const u32x4*)(GB + off), g2);
; #pragma unroll
;         for (int e = 0; e < 8; ++e) { const float cur = a[e] * b[e]; o[e] = g1[e] * (w0[e] * p2[e] + w1[e] * p1[e] + w2[e] * cur) * g2[e]; p2[e] = p1[e]; p1[e] = cur; }
;         u32x4 w; w.x = pk2(o[0], o[1]); w.y = pk2(o[2], o[3]); w.z = pk2(o[4], o[5]); w.w = pk2(o[6], o[7]);
;         *(u32x4*)(OB + off) = w;
;     }
	v_lshlrev_b32_e32 v80, 16, v24
	v_and_b32_e32 v81, 0xffff0000, v24
	v_pk_mul_f32 v[44:45], v[44:45], v[78:79]
	v_and_b32_e32 v51, 0xffff0000, v63
	v_pk_mul_f32 v[78:79], v[44:45], v[80:81]
	v_lshlrev_b32_e32 v44, 16, v59
	v_and_b32_e32 v45, 0xffff0000, v59
	global_load_dwordx4 v[74:77], v88, s[44:45]
	v_pk_mul_f32 v[62:63], v[44:45], v[50:51]
	v_pk_mul_f32 v[44:45], v[22:23], v[38:39]
	v_lshlrev_b32_e32 v28, 16, v29
	v_pk_fma_f32 v[44:45], v[14:15], v[48:49], v[44:45]
	v_and_b32_e32 v29, 0xffff0000, v29
	v_pk_fma_f32 v[44:45], v[18:19], v[62:63], v[44:45]
	v_lshlrev_b32_e32 v24, 16, v25
	v_and_b32_e32 v25, 0xffff0000, v25
	v_pk_mul_f32 v[28:29], v[44:45], v[28:29]
	v_lshlrev_b32_e32 v44, 16, v30
	v_pk_mul_f32 v[80:81], v[28:29], v[24:25]
	v_lshlrev_b32_e32 v24, 16, v60
	v_and_b32_e32 v25, 0xffff0000, v60
	v_lshlrev_b32_e32 v28, 16, v64
	v_and_b32_e32 v29, 0xffff0000, v64
	v_pk_mul_f32 v[82:83], v[24:25], v[28:29]
	v_pk_mul_f32 v[24:25], v[4:5], v[40:41]
	v_and_b32_e32 v45, 0xffff0000, v30
	v_pk_fma_f32 v[24:25], v[0:1], v[46:47], v[24:25]
	v_lshlrev_b32_e32 v48, 16, v26
	v_and_b32_e32 v49, 0xffff0000, v26
	v_pk_fma_f32 v[24:25], v[8:9], v[82:83], v[24:25]
	v_or_b32_e32 v26, v56, v174
	v_pk_mul_f32 v[24:25], v[24:25], v[44:45]
	v_lshlrev_b32_e32 v86, 1, v26
	v_pk_mul_f32 v[84:85], v[24:25], v[48:49]
	global_load_dwordx4 v[44:47], v86, s[40:41]
	global_load_dwordx4 v[48:51], v86, s[42:43]
	global_load_dwordx4 v[56:59], v86, s[44:45]
	v_lshlrev_b32_e32 v24, 16, v61
	v_and_b32_e32 v25, 0xffff0000, v61
	v_lshlrev_b32_e32 v60, 16, v65
	v_and_b32_e32 v61, 0xffff0000, v65
	v_lshlrev_b32_e32 v64, 16, v31
	v_and_b32_e32 v65, 0xffff0000, v31
	global_load_dwordx4 v[28:31], v86, s[38:39]
	v_pk_mul_f32 v[60:61], v[24:25], v[60:61]
	v_pk_mul_f32 v[24:25], v[6:7], v[42:43]
	v_lshlrev_b32_e32 v26, 16, v27
	v_pk_fma_f32 v[24:25], v[2:3], v[32:33], v[24:25]
	v_and_b32_e32 v27, 0xffff0000, v27
	v_pk_fma_f32 v[24:25], v[10:11], v[60:61], v[24:25]
	s_nop 0
	v_pk_mul_f32 v[24:25], v[24:25], v[64:65]
	s_waitcnt vmcnt(4)
	v_lshlrev_b32_e32 v64, 16, v74
	v_pk_mul_f32 v[32:33], v[24:25], v[26:27]
	v_cvt_pk_bf16_f32 v24, v78, v79
	v_cvt_pk_bf16_f32 v25, v80, v81
	v_cvt_pk_bf16_f32 v26, v84, v85
	v_cvt_pk_bf16_f32 v27, v32, v33
	global_store_dwordx4 v90, v[24:27], s[46:47]
	v_lshlrev_b32_e32 v32, 16, v70
	v_and_b32_e32 v33, 0xffff0000, v70
	v_lshlrev_b32_e32 v24, 16, v52
	v_and_b32_e32 v25, 0xffff0000, v52
	v_lshlrev_b32_e32 v26, 16, v66
	v_and_b32_e32 v27, 0xffff0000, v66
	v_pk_mul_f32 v[78:79], v[24:25], v[26:27]
	v_pk_mul_f32 v[24:25], v[20:21], v[34:35]
	v_lshlrev_b32_e32 v26, 16, v53
	v_pk_fma_f32 v[24:25], v[12:13], v[36:37], v[24:25]
	v_and_b32_e32 v27, 0xffff0000, v53
	v_pk_fma_f32 v[24:25], v[16:17], v[78:79], v[24:25]
	v_lshlrev_b32_e32 v36, 16, v71
	v_pk_mul_f32 v[24:25], v[24:25], v[32:33]
	v_lshlrev_b32_e32 v32, 16, v67
	v_and_b32_e32 v33, 0xffff0000, v67
	v_pk_mul_f32 v[32:33], v[26:27], v[32:33]
	v_pk_mul_f32 v[26:27], v[22:23], v[62:63]
	v_and_b32_e32 v37, 0xffff0000, v71
	v_pk_fma_f32 v[26:27], v[14:15], v[38:39], v[26:27]
	v_lshlrev_b32_e32 v38, 16, v68
	v_pk_fma_f32 v[26:27], v[18:19], v[32:33], v[26:27]
	v_and_b32_e32 v39, 0xffff0000, v68
	v_pk_mul_f32 v[26:27], v[26:27], v[36:37]
	v_lshlrev_b32_e32 v36, 16, v54
	v_and_b32_e32 v37, 0xffff0000, v54
	v_pk_mul_f32 v[36:37], v[36:37], v[38:39]
	v_pk_mul_f32 v[38:39], v[4:5], v[82:83]
	v_lshlrev_b32_e32 v52, 16, v75
	v_and_b32_e32 v53, 0xffff0000, v75
	v_pk_fma_f32 v[38:39], v[0:1], v[40:41], v[38:39]
	v_pk_mul_f32 v[26:27], v[26:27], v[52:53]
	v_lshlrev_b32_e32 v52, 16, v72
	v_and_b32_e32 v53, 0xffff0000, v72
	v_pk_fma_f32 v[38:39], v[8:9], v[36:37], v[38:39]
	v_lshlrev_b32_e32 v40, 16, v55
	v_pk_mul_f32 v[38:39], v[38:39], v[52:53]
	v_and_b32_e32 v41, 0xffff0000, v55
	v_lshlrev_b32_e32 v52, 16, v69
	v_and_b32_e32 v53, 0xffff0000, v69
	v_pk_mul_f32 v[40:41], v[40:41], v[52:53]
	v_pk_mul_f32 v[52:53], v[6:7], v[60:61]
	v_and_b32_e32 v65, 0xffff0000, v74
	v_pk_fma_f32 v[42:43], v[2:3], v[42:43], v[52:53]
	v_pk_mul_f32 v[24:25], v[24:25], v[64:65]
	v_lshlrev_b32_e32 v64, 16, v76
	v_and_b32_e32 v65, 0xffff0000, v76
	v_lshlrev_b32_e32 v54, 16, v73
	v_and_b32_e32 v55, 0xffff0000, v73
	v_pk_fma_f32 v[42:43], v[10:11], v[40:41], v[42:43]
	v_pk_mul_f32 v[38:39], v[38:39], v[64:65]
	v_lshlrev_b32_e32 v64, 16, v77
	v_and_b32_e32 v65, 0xffff0000, v77
	v_pk_mul_f32 v[42:43], v[42:43], v[54:55]
	v_cvt_pk_bf16_f32 v24, v24, v25
	v_pk_mul_f32 v[42:43], v[42:43], v[64:65]
	v_cvt_pk_bf16_f32 v25, v26, v27
	v_cvt_pk_bf16_f32 v26, v38, v39
	v_cvt_pk_bf16_f32 v27, v42, v43
	global_store_dwordx4 v88, v[24:27], s[46:47]
	v_pk_mul_f32 v[20:21], v[20:21], v[78:79]
	v_pk_mul_f32 v[4:5], v[4:5], v[36:37]
	s_waitcnt vmcnt(5)
	v_lshlrev_b32_e32 v24, 16, v44
	v_and_b32_e32 v25, 0xffff0000, v44
	s_waitcnt vmcnt(4)
	v_lshlrev_b32_e32 v26, 16, v48
	v_and_b32_e32 v27, 0xffff0000, v48
	v_pk_mul_f32 v[24:25], v[24:25], v[26:27]
	v_pk_fma_f32 v[12:13], v[12:13], v[34:35], v[20:21]
	v_lshlrev_b32_e32 v20, 16, v49
	v_pk_fma_f32 v[12:13], v[16:17], v[24:25], v[12:13]
	v_lshlrev_b32_e32 v16, 16, v45
	v_and_b32_e32 v17, 0xffff0000, v45
	v_and_b32_e32 v21, 0xffff0000, v49
	v_pk_mul_f32 v[16:17], v[16:17], v[20:21]
	v_pk_mul_f32 v[20:21], v[22:23], v[32:33]
	v_pk_fma_f32 v[0:1], v[0:1], v[82:83], v[4:5]
	v_pk_fma_f32 v[14:15], v[14:15], v[62:63], v[20:21]
	s_waitcnt vmcnt(2)
	v_lshlrev_b32_e32 v20, 16, v30
	v_pk_fma_f32 v[14:15], v[18:19], v[16:17], v[14:15]
	v_lshlrev_b32_e32 v16, 16, v46
	v_and_b32_e32 v17, 0xffff0000, v46
	v_lshlrev_b32_e32 v18, 16, v50
	v_and_b32_e32 v19, 0xffff0000, v50
	v_pk_mul_f32 v[16:17], v[16:17], v[18:19]
	v_and_b32_e32 v21, 0xffff0000, v30
	v_pk_fma_f32 v[0:1], v[8:9], v[16:17], v[0:1]
	v_lshlrev_b32_e32 v22, 16, v58
	v_and_b32_e32 v23, 0xffff0000, v58
	v_pk_mul_f32 v[0:1], v[0:1], v[20:21]
	v_lshlrev_b32_e32 v8, 16, v51
	v_pk_mul_f32 v[4:5], v[0:1], v[22:23]
	v_lshlrev_b32_e32 v0, 16, v47
	v_and_b32_e32 v1, 0xffff0000, v47
	v_and_b32_e32 v9, 0xffff0000, v51
	v_pk_mul_f32 v[6:7], v[6:7], v[40:41]
	v_pk_mul_f32 v[0:1], v[0:1], v[8:9]
	v_pk_fma_f32 v[2:3], v[2:3], v[60:61], v[6:7]
	v_lshlrev_b32_e32 v38, 16, v28
	v_and_b32_e32 v39, 0xffff0000, v28
	v_lshlrev_b32_e32 v24, 16, v29
	v_and_b32_e32 v25, 0xffff0000, v29
	v_lshlrev_b32_e32 v16, 16, v31
	v_and_b32_e32 v17, 0xffff0000, v31
	v_pk_fma_f32 v[0:1], v[10:11], v[0:1], v[2:3]
	v_lshlrev_b32_e32 v42, 16, v56
	v_and_b32_e32 v43, 0xffff0000, v56
	v_pk_mul_f32 v[12:13], v[12:13], v[38:39]
	v_lshlrev_b32_e32 v26, 16, v57
	v_and_b32_e32 v27, 0xffff0000, v57
	v_pk_mul_f32 v[14:15], v[14:15], v[24:25]
	v_lshlrev_b32_e32 v18, 16, v59
	v_and_b32_e32 v19, 0xffff0000, v59
	v_pk_mul_f32 v[0:1], v[0:1], v[16:17]
	v_pk_mul_f32 v[12:13], v[12:13], v[42:43]
	v_pk_mul_f32 v[14:15], v[14:15], v[26:27]
	v_pk_mul_f32 v[6:7], v[0:1], v[18:19]
	v_cvt_pk_bf16_f32 v0, v12, v13
	v_cvt_pk_bf16_f32 v1, v14, v15
	v_cvt_pk_bf16_f32 v2, v4, v5
	v_cvt_pk_bf16_f32 v3, v6, v7
	global_store_dwordx4 v86, v[0:3], s[46:47]

; #define LAS __attribute__((address_space(3)))
; __device__ __forceinline__ void attn_item(const bf16_t* __restrict__ Q, const bf16_t* __restrict__ Kb, const bf16_t* __restrict__ VT, const bf16_t* __restrict__ GA, ...
;     ...
;     const bf16_t* tg = half ? VT + (size_t)(h * 64 + rl) * PT + tk0 + cl * 8 : Kb + (size_t)(tk0 + rl) * DH + h * 64 + cl * 8;
;     const size_t rstep = half ? (size_t)8 * PT : (size_t)8 * DH;
;     const size_t tstep = half ? (size_t)64 : (size_t)64 * DH;
;     const int stoff = (half ? 64 * ATP : 0) + rl * ATP + cl * 16;
;     u32x4 tr[8];
; #pragma unroll
;     for (int i = 0; i < 8; ++i) tr[i] = *(const u32x4*)(tg + i * rstep);
;     bf16x8 qf[4];
;     { const bf16_t* qp = Q + (size_t)(tokq + r) * DH + h * 64 + 8 * hh;
; #pragma unroll
;       for (int d0 = 0; d0 < 4; ++d0) qf[d0] = *(const bf16x8*)(qp + d0 * 16); }
;     int buf = 0;
; #pragma unroll
;     for (int i = 0; i < 8; ++i) *(LAS u32x4*)(pl + stoff + 8 * i * ATP) = tr[i];
;     tg += (jmin + 1 <= 8) ? tstep : (size_t)0;
; #pragma unroll
;     for (int i = 0; i < 8; ++i) tr[i] = *(const u32x4*)(tg + i * rstep);
;     ATT_BAR();
;     f32x16 o0, o1, cinit;
; #pragma unroll
;     for (int i = 0; i < 16; ++i) { o0[i] = 0.f; o1[i] = 0.f; }
;     constexpr float ATT_THR = 8.f;
;     float mref = 0.f, lrun = 0.f;
;     const float cfar = btab[NREL - 1];
; #pragma unroll
;     for (int i = 0; i < 16; ++i) cinit[i] = cfar;
;     for (int j = jmin; j <= 8; ++j) {
;         const LAS unsigned char* kfp = pl + buf * ATT_WAVE_LDS + pr * ATP + 16 * hh;
;         const LAS unsigned char* vfp = pl + buf * ATT_WAVE_LDS + 64 * ATP + r * ATP + 16 * hh;
;         f32x16 s0, s1;
;         if (j <= 3) {
;             const bf16x8 k0 = *(const LAS bf16x8*)(kfp), k1 = *(const LAS bf16x8*)(kfp + 32 * ATP);
;             s0 = MFMA32(k0, qf[0], cinit); s1 = MFMA32(k1, qf[0], cinit);
;         } else {
;             const LAS float* bp = btab + (qloc + 64 * (8 - j) + 63 - 8 * hh);
; #pragma unroll
;             for (int i = 0; i < 16; ++i) {
;                 const int key = (i & 3) + 4 * ((i >> 2) & 1) + 16 * (i >> 3);
;                 s0[i] = bp[-key] - mref; s1[i] = bp[-key - 32] - mref;
;             }
;             const bf16x8 k0 = *(const LAS bf16x8*)(kfp), k1 = *(const LAS bf16x8*)(kfp + 32 * ATP);
;             s0 = MFMA32(k0, qf[0], s0); s1 = MFMA32(k1, qf[0], s1);
.LBB0_248:
	v_lshlrev_b32_e32 v132, 1, v138
	s_lshl_b32 s66, s66, 1
	v_lshl_add_u64 v[0:1], v[0:1], 0, v[132:133]
	s_mov_b32 s68, s66
	s_mov_b32 s69, s29
	v_lshl_add_u64 v[2:3], v[0:1], 0, s[68:69]
	global_load_dwordx4 v[34:37], v[0:1], off
	global_load_dwordx4 v[38:41], v[2:3], off
	v_lshl_add_u64 v[2:3], v[2:3], 0, s[68:69]
	v_lshl_add_u64 v[4:5], v[2:3], 0, s[68:69]
	global_load_dwordx4 v[42:45], v[2:3], off
	global_load_dwordx4 v[46:49], v[4:5], off
	v_lshl_add_u64 v[2:3], v[4:5], 0, s[68:69]
	v_lshl_add_u64 v[4:5], v[2:3], 0, s[68:69]
	global_load_dwordx4 v[50:53], v[2:3], off
	global_load_dwordx4 v[54:57], v[4:5], off
	v_lshl_add_u64 v[2:3], v[4:5], 0, s[68:69]
	v_lshl_add_u64 v[4:5], v[2:3], 0, s[68:69]
	global_load_dwordx4 v[58:61], v[2:3], off
	global_load_dwordx4 v[62:65], v[4:5], off
	v_add_u32_e32 v186, s65, v164
	s_lshl_b32 s7, s71, 6
	s_add_i32 s7, s7, s70
	v_and_b32_e32 v2, 64, v182
	s_or_b32 s65, s7, s78
	v_or_b32_e32 v226, s65, v131
	v_ashrrev_i32_e32 v227, 31, v226
	v_lshlrev_b64 v[226:227], 11, v[226:227]
	v_lshl_add_u64 v[226:227], s[24:25], 0, v[226:227]
	v_lshl_add_u64 v[226:227], s[8:9], 1, v[226:227]
	v_lshlrev_b32_e32 v228, 1, v130
	v_mov_b32_e32 v229, 0
	v_lshl_add_u64 v[226:227], v[226:227], 0, v[228:229]
	global_load_dwordx4 v[82:85], v[226:227], off
	global_load_dwordx4 v[86:89], v[226:227], off offset:32
	global_load_dwordx4 v[90:93], v[226:227], off offset:64
	global_load_dwordx4 v[94:97], v[226:227], off offset:96
	v_xor_b32_e32 v184, 32, v182
	v_mov_b32_e32 v33, 0
	v_mov_b32_e32 v32, 0
	v_mov_b32_e32 v31, 0
	v_mov_b32_e32 v30, 0
	v_mov_b32_e32 v29, 0
	v_mov_b32_e32 v28, 0
	v_mov_b32_e32 v27, 0
	v_mov_b32_e32 v26, 0
	v_mov_b32_e32 v25, 0
	v_mov_b32_e32 v24, 0
	v_mov_b32_e32 v23, 0
	v_mov_b32_e32 v22, 0
	v_mov_b32_e32 v21, 0
	v_mov_b32_e32 v20, 0
	v_mov_b32_e32 v19, 0
	v_mov_b32_e32 v18, 0
	v_mov_b32_e32 v17, 0
	v_mov_b32_e32 v16, 0
	v_mov_b32_e32 v15, 0
	v_mov_b32_e32 v14, 0
	v_mov_b32_e32 v13, 0
	v_mov_b32_e32 v12, 0
	v_mov_b32_e32 v11, 0
	v_mov_b32_e32 v10, 0
	v_mov_b32_e32 v9, 0
	v_mov_b32_e32 v8, 0
	v_mov_b32_e32 v7, 0
	v_mov_b32_e32 v6, 0
	v_mov_b32_e32 v5, 0
	v_add_u32_e32 v185, 64, v2
	s_cmp_gt_i32 s33, 8
	v_mov_b32_e32 v4, 0
	v_mov_b32_e32 v3, 0
	v_mov_b32_e32 v2, 0
	v_mov_b32_e32 v187, 0
	s_waitcnt vmcnt(0)
	ds_write_b128 v186, v[34:37]
	ds_write_b128 v186, v[38:41] offset:1152
	ds_write_b128 v186, v[42:45] offset:2304
	ds_write_b128 v186, v[46:49] offset:3456
	ds_write_b128 v186, v[50:53] offset:4608
	ds_write_b128 v186, v[54:57] offset:5760
	ds_write_b128 v186, v[58:61] offset:6912
	ds_write_b128 v186, v[62:65] offset:8064
	s_waitcnt lgkmcnt(0)
	s_barrier
	s_cbranch_scc1 .LBB0_217
	s_cmp_lt_i32 s33, 8
	v_or_b32_e32 v2, s65, v131
	s_cselect_b64 s[70:71], -1, 0
	v_ashrrev_i32_e32 v3, 31, v2
	s_and_b64 s[72:73], s[70:71], exec
	v_lshlrev_b64 v[2:3], 11, v[2:3]
	s_cselect_b32 s7, s64, 0
	v_lshl_add_u64 v[2:3], s[24:25], 0, v[2:3]
	s_lshl_b32 s28, s7, 1
	v_lshl_add_u64 v[2:3], s[8:9], 1, v[2:3]
	v_lshlrev_b32_e32 v132, 1, v130
	v_lshl_add_u64 v[80:81], v[0:1], 0, s[28:29]
	v_lshl_add_u64 v[2:3], v[2:3], 0, v[132:133]
	v_lshl_add_u64 v[0:1], v[80:81], 0, s[68:69]
	v_lshl_add_u64 v[2:3], v[0:1], 0, s[68:69]
	global_load_dwordx4 v[48:51], v[80:81], off
	global_load_dwordx4 v[52:55], v[0:1], off
	global_load_dwordx4 v[56:59], v[2:3], off
	v_lshl_add_u64 v[0:1], v[2:3], 0, s[68:69]
	v_lshl_add_u64 v[2:3], v[0:1], 0, s[68:69]
	global_load_dwordx4 v[60:63], v[0:1], off
	global_load_dwordx4 v[64:67], v[2:3], off
	v_lshl_add_u64 v[0:1], v[2:3], 0, s[68:69]
	v_lshl_add_u64 v[2:3], v[0:1], 0, s[68:69]
	global_load_dwordx4 v[68:71], v[0:1], off
	global_load_dwordx4 v[72:75], v[2:3], off
	v_lshl_add_u64 v[0:1], v[2:3], 0, s[68:69]
	global_load_dwordx4 v[76:79], v[0:1], off
	v_mov_b32_e32 v0, s75
	ds_read_b32 v0, v0 offset:1276
	s_cmp_lt_i32 s33, 4
	s_mov_b64 s[72:73], -1
	s_cbranch_scc1 .LBB0_251
	v_lshl_or_b32 v1, s33, 6, v130
	v_sub_u32_e32 v1, v173, v1
	v_lshl_add_u32 v1, v1, 2, s75
	v_add_u32_e32 v2, 0x8f8, v1
	v_add_u32_e32 v4, 0x878, v1
	v_add_u32_e32 v6, 0x8f0, v1
	v_add_u32_e32 v8, 0x870, v1
	v_add_u32_e32 v10, 0x8e8, v1
	v_add_u32_e32 v12, 0x868, v1
	v_add_u32_e32 v14, 0x8e0, v1
	v_add_u32_e32 v16, 0x860, v1
	ds_read2_b32 v[2:3], v2 offset1:1
	ds_read2_b32 v[4:5], v4 offset1:1
	ds_read2_b32 v[6:7], v6 offset1:1
	ds_read2_b32 v[8:9], v8 offset1:1
	ds_read2_b32 v[10:11], v10 offset1:1
	ds_read2_b32 v[12:13], v12 offset1:1
	ds_read2_b32 v[14:15], v14 offset1:1
	ds_read2_b32 v[40:41], v16 offset1:1
	v_add_u32_e32 v16, 0x8b8, v1
	v_add_u32_e32 v17, 0x838, v1
	v_add_u32_e32 v18, 0x8b0, v1
	v_add_u32_e32 v19, 0x830, v1
	ds_read2_b32 v[26:27], v16 offset1:1
	ds_read2_b32 v[42:43], v17 offset1:1
	ds_read2_b32 v[28:29], v18 offset1:1
	ds_read2_b32 v[44:45], v19 offset1:1
	v_add_u32_e32 v16, 0x8a8, v1
	ds_read2_b32 v[30:31], v16 offset1:1
	v_add_u32_e32 v33, 0x8a0, v1
	v_add_u32_e32 v32, 0x828, v1
	s_waitcnt lgkmcnt(12)
	v_mov_b32_e32 v16, v3
	v_mov_b32_e32 v17, v2
	s_waitcnt lgkmcnt(8)
	v_mov_b32_e32 v20, v11
	v_mov_b32_e32 v21, v10
	s_waitcnt lgkmcnt(6)
	v_mov_b32_e32 v22, v15
	v_mov_b32_e32 v23, v14
	v_add_u32_e32 v1, 0x820, v1
	ds_read2_b32 v[2:3], v33 offset1:1
	ds_read2_b32 v[10:11], v32 offset1:1
	ds_read2_b32 v[14:15], v1 offset1:1
	v_mov_b32_e32 v18, v7
	v_mov_b32_e32 v19, v6
	s_waitcnt lgkmcnt(7)
	v_mov_b32_e32 v24, v27
	v_mov_b32_e32 v25, v26
	s_waitcnt lgkmcnt(5)
	v_mov_b32_e32 v26, v29
	v_mov_b32_e32 v27, v28
	s_waitcnt lgkmcnt(3)
	v_mov_b32_e32 v28, v31
	v_mov_b32_e32 v29, v30
	s_waitcnt lgkmcnt(2)
	v_mov_b32_e32 v30, v3
	v_mov_b32_e32 v31, v2
	v_mov_b32_e32 v32, v5
	v_mov_b32_e32 v33, v4
	ds_read_b128 v[2:5], v183
	v_mov_b32_e32 v34, v9
	v_mov_b32_e32 v35, v8
	ds_read_b128 v[6:9], v183 offset:4608
	v_mov_b32_e32 v36, v13
	v_mov_b32_e32 v37, v12
	v_mov_b32_e32 v38, v41
	v_mov_b32_e32 v39, v40
	v_mov_b32_e32 v40, v43
	v_mov_b32_e32 v41, v42
	v_mov_b32_e32 v42, v45
	v_mov_b32_e32 v43, v44
	s_waitcnt lgkmcnt(3)
	v_mov_b32_e32 v44, v11
	v_mov_b32_e32 v45, v10
	s_waitcnt lgkmcnt(2)
	v_mov_b32_e32 v46, v15
	v_mov_b32_e32 v47, v14
	s_waitcnt vmcnt(11) lgkmcnt(1)
	v_mfma_f32_32x32x16_bf16 v[16:31], v[2:5], v[82:85], v[16:31]
	s_mov_b64 s[72:73], 0
	s_waitcnt lgkmcnt(0)
	v_mfma_f32_32x32x16_bf16 v[32:47], v[6:9], v[82:85], v[32:47]

; #define PG8_STAGE(bufoff, gbase, voff) do { _Pragma("unroll") for (int _i = 0; _i < 2; ++_i) \
;         __builtin_amdgcn_global_load_lds((const unsigned*)((const char*)(gbase) + (voff)[_i]), (LAS unsigned*)(lds + (bufoff) + ldsw + _i * 8192), 16, 0, 0); } while (0)
; #define PG8_WAIT_V(n) asm volatile("s_waitcnt vmcnt(" #n ")" ::: "memory")
; #define PG8_BAR __builtin_amdgcn_s_barrier()
; template <class Epi, class Sched, bool ALIGN_EPI, bool I8 = false>
; __device__ __forceinline__ void gemm_phase(LAS unsigned char* lds, const Gemm g, const Sched& S, const Epi& E) {
;     ...
;                 for (int n = 0; n < 2; ++n) acc[a][b][m][n] = (f32x4){0.f, 0.f, 0.f, 0.f};
;     bf16x8 At[4][2], B0[2][2], B1[2][2];
;     const char* cA = (const char*)g.A + (size_t)cur.z * g.zA + (size_t)cur.pm * tstep; const char* cB = (const char*)g.Bt + (size_t)cur.z * g.zB + (size_t)cur.pn * tstep;
;     PG8_STAGE(PG8_SB(0, 0), cB, voffB); PG8_STAGE(PG8_SB(0, 1), cB + hstep, voffB); PG8_STAGE(PG8_SA(0, 0), cA, voffA); PG8_STAGE(PG8_SA(0, 1), cA + hstep, voffA);
;     if (wr == 1) PG8_BAR;
;     PG8_WAIT_V(2); PG8_BAR;
;     PG8_STAGE(PG8_SB(1, 0), cB + kstep, voffB); PG8_STAGE(PG8_SA(1, 0), cA + kstep, voffA); PG8_STAGE(PG8_SB(1, 1), cB + hstep + kstep, voffB);
;     PG8_WAIT_V(6); PG8_BAR;
.LBB0_321:
	s_add_u32 s12, s20, 0x25200000
	s_addc_u32 s13, s21, 0
	s_add_u32 s14, s20, 0x17200000
	v_and_b32_e32 v13, 15, v217
	v_lshlrev_b32_e32 v14, 1, v11
	v_lshlrev_b32_e32 v15, 2, v217
	s_sext_i32_i8 s5, s2
	s_addc_u32 s15, s21, 0
	v_lshl_or_b32 v178, s3, 6, v13
	v_lshl_or_b32 v13, v13, 6, v14
	s_lshl_b32 s2, s3, 13
	v_and_b32_e32 v15, 32, v15
	v_bitop3_b32 v13, v13, s2, v15 bitop3:0xde
	s_lshl_b32 s2, s16, 5
	s_mov_b64 s[16:17], 0x80
	s_and_b32 s7, s2, 0x60
	v_lshlrev_b32_e32 v16, 6, v217
	s_movk_i32 s2, 0x3c0
	s_add_i32 m0, s55, 0x18000
	v_lshl_add_u64 v[6:7], v[6:7], 0, s[16:17]
	v_and_or_b32 v14, v16, s2, v14
	s_lshl_b32 s2, s7, 7
	global_load_lds_dwordx4 v[6:7], off
	v_lshl_add_u64 v[4:5], v[4:5], 0, s[16:17]
	s_add_i32 m0, s55, 0x1a000
	s_add_i32 s59, s55, 0x8000
	s_add_i32 s60, s55, 0xa000
	v_bitop3_b32 v179, s2, v14, v15 bitop3:0xf6
	global_load_lds_dwordx4 v[4:5], off
	v_lshl_add_u64 v[0:1], v[0:1], 0, s[16:17]
	s_mov_b32 m0, s59
	s_add_u32 s2, s46, 0x40080
	global_load_lds_dwordx4 v[0:1], off
	v_lshl_add_u64 v[0:1], v[2:3], 0, s[16:17]
	s_mov_b32 m0, s60
	s_addc_u32 s3, s47, 0
	global_load_lds_dwordx4 v[0:1], off
	s_add_i32 m0, s55, 0x1c000
	v_lshl_add_u64 v[0:1], s[2:3], 0, v[162:163]
	global_load_lds_dwordx4 v[0:1], off
	v_lshl_add_u64 v[0:1], s[2:3], 0, v[166:167]
	s_add_i32 m0, s55, 0x1e000
	s_cmpk_lt_u32 s18, 0x100
	global_load_lds_dwordx4 v[0:1], off
	v_lshlrev_b32_e32 v0, 8, v217
	v_and_b32_e32 v0, 0x38000, v0
	v_lshlrev_b32_e32 v1, 11, v10
	v_or3_b32 v0, v8, v0, v1
	v_add_u32_e32 v168, v0, v9
	v_lshlrev_b32_e32 v0, 4, v12
	s_waitcnt vmcnt(8)
	s_barrier
	s_waitcnt vmcnt(6)
	v_and_b32_e32 v0, 0x78000, v0
	v_or3_b32 v0, v8, v0, v1
	s_cselect_b64 s[18:19], -1, 0
	v_or_b32_e32 v180, s7, v11
	v_mov_b32_e32 v169, v163
	v_add_u32_e32 v170, v0, v9
	v_mov_b32_e32 v171, v163
	v_mov_b64_e32 v[172:173], 0x200
	v_mov_b64_e32 v[174:175], 0x1ff
	s_add_i32 s61, 0, 0x10000
	s_add_i32 s62, 0, 0x14000
	v_add_u32_e32 v181, 0, v13
	s_movk_i32 s63, 0x3000
	s_mov_b32 s64, 0x30000
	s_mov_b32 s65, 0x60000
	s_mov_b32 s66, 0x90000
	s_mov_b32 s67, 0x180000
	s_mov_b32 s68, 0x1b0000
	s_mov_b32 s69, 0x1e0000
	s_mov_b32 s70, 0x210000
	s_mov_b64 s[24:25], 0x80000
	s_mov_b32 s71, 0x80000
	s_mov_b64 s[26:27], 0x90000
	s_mov_b64 s[28:29], 0xa0000
	s_mov_b32 s72, 0xa0000
	s_mov_b64 s[30:31], 0xb0000
	s_mov_b32 s73, 0xb0000
	s_mov_b32 s74, 0x31000
	s_mov_b32 s75, 0x61000
	s_mov_b32 s76, 0x91000
	s_mov_b32 s77, 0x181000
	s_mov_b32 s78, 0x1b1000
	s_mov_b32 s79, 0x1e1000
	s_mov_b32 s80, 0x211000
	s_mov_b32 s81, 0
	v_mov_b32_e32 v0, v163
	v_mov_b32_e32 v1, v163
	v_mov_b32_e32 v2, v163
	v_mov_b32_e32 v3, v163
	v_mov_b32_e32 v4, v163
	v_mov_b32_e32 v5, v163
	v_mov_b32_e32 v6, v163
	v_mov_b32_e32 v7, v163
	v_mov_b32_e32 v8, v163
	v_mov_b32_e32 v9, v163
	v_mov_b32_e32 v10, v163
	v_mov_b32_e32 v11, v163
	v_mov_b32_e32 v12, v163
	v_mov_b32_e32 v13, v163
	v_mov_b32_e32 v14, v163
	v_mov_b32_e32 v15, v163
	v_mov_b32_e32 v16, v163
	v_mov_b32_e32 v17, v163
	v_mov_b32_e32 v18, v163
	v_mov_b32_e32 v19, v163
	v_mov_b32_e32 v20, v163
	v_mov_b32_e32 v21, v163
	v_mov_b32_e32 v22, v163
	v_mov_b32_e32 v23, v163
	v_mov_b32_e32 v24, v163
	v_mov_b32_e32 v25, v163
	v_mov_b32_e32 v26, v163
	v_mov_b32_e32 v27, v163
	v_mov_b32_e32 v28, v163
	v_mov_b32_e32 v29, v163
	v_mov_b32_e32 v30, v163
	v_mov_b32_e32 v31, v163
	v_mov_b32_e32 v32, v163
	v_mov_b32_e32 v33, v163
	v_mov_b32_e32 v34, v163
	v_mov_b32_e32 v35, v163
	v_mov_b32_e32 v36, v163
	v_mov_b32_e32 v37, v163
	v_mov_b32_e32 v38, v163
	v_mov_b32_e32 v39, v163
	v_mov_b32_e32 v40, v163
	v_mov_b32_e32 v41, v163
	v_mov_b32_e32 v42, v163
	v_mov_b32_e32 v43, v163
	v_mov_b32_e32 v44, v163
	v_mov_b32_e32 v45, v163
	v_mov_b32_e32 v46, v163
	v_mov_b32_e32 v47, v163
	v_mov_b32_e32 v48, v163
	v_mov_b32_e32 v49, v163
	v_mov_b32_e32 v50, v163
	v_mov_b32_e32 v51, v163
	v_mov_b32_e32 v52, v163
	v_mov_b32_e32 v53, v163
	v_mov_b32_e32 v54, v163
	v_mov_b32_e32 v55, v163
	v_mov_b32_e32 v56, v163
	v_mov_b32_e32 v57, v163
	v_mov_b32_e32 v58, v163
	v_mov_b32_e32 v59, v163
	v_mov_b32_e32 v60, v163
	v_mov_b32_e32 v61, v163
	v_mov_b32_e32 v62, v163
	v_mov_b32_e32 v63, v163
	v_mov_b32_e32 v64, v163
	v_mov_b32_e32 v65, v163
	v_mov_b32_e32 v66, v163
	v_mov_b32_e32 v67, v163
	v_mov_b32_e32 v68, v163
	v_mov_b32_e32 v69, v163
	v_mov_b32_e32 v70, v163
	v_mov_b32_e32 v71, v163
	v_mov_b32_e32 v72, v163
	v_mov_b32_e32 v73, v163
	v_mov_b32_e32 v74, v163
	v_mov_b32_e32 v75, v163
	v_mov_b32_e32 v76, v163
	v_mov_b32_e32 v77, v163
	v_mov_b32_e32 v78, v163
	v_mov_b32_e32 v79, v163
	v_mov_b32_e32 v80, v163
	v_mov_b32_e32 v81, v163
	v_mov_b32_e32 v82, v163
	v_mov_b32_e32 v83, v163
	v_mov_b32_e32 v84, v163
	v_mov_b32_e32 v85, v163
	v_mov_b32_e32 v86, v163
	v_mov_b32_e32 v87, v163
	v_mov_b32_e32 v88, v163
	v_mov_b32_e32 v89, v163
	v_mov_b32_e32 v90, v163
	v_mov_b32_e32 v91, v163
	v_mov_b32_e32 v92, v163
	v_mov_b32_e32 v93, v163
	v_mov_b32_e32 v94, v163
	v_mov_b32_e32 v95, v163
	v_mov_b32_e32 v96, v163
	v_mov_b32_e32 v97, v163
	v_mov_b32_e32 v98, v163
	v_mov_b32_e32 v99, v163
	v_mov_b32_e32 v100, v163
	v_mov_b32_e32 v101, v163
	v_mov_b32_e32 v102, v163
	v_mov_b32_e32 v103, v163
	v_mov_b32_e32 v104, v163
	v_mov_b32_e32 v105, v163
	v_mov_b32_e32 v106, v163
	v_mov_b32_e32 v107, v163
	v_mov_b32_e32 v108, v163
	v_mov_b32_e32 v109, v163
	v_mov_b32_e32 v110, v163
	v_mov_b32_e32 v111, v163
	v_mov_b32_e32 v112, v163
	v_mov_b32_e32 v113, v163
	v_mov_b32_e32 v114, v163
	v_mov_b32_e32 v115, v163
	v_mov_b32_e32 v116, v163
	v_mov_b32_e32 v117, v163
	v_mov_b32_e32 v118, v163
	v_mov_b32_e32 v119, v163
	v_mov_b32_e32 v120, v163
	v_mov_b32_e32 v121, v163
	v_mov_b32_e32 v122, v163
	v_mov_b32_e32 v123, v163
	v_mov_b32_e32 v124, v163
	v_mov_b32_e32 v125, v163
	v_mov_b32_e32 v126, v163
	v_mov_b32_e32 v127, v163
	s_barrier
	s_branch .LBB0_324

; #define PG8_STAGE(bufoff, gbase, voff) do { _Pragma("unroll") for (int _i = 0; _i < 2; ++_i) \
;         __builtin_amdgcn_global_load_lds((const unsigned*)((const char*)(gbase) + (voff)[_i]), (LAS unsigned*)(lds + (bufoff) + ldsw + _i * 8192), 16, 0, 0); } while (0)
; #define PG8_WAIT_V(n) asm volatile("s_waitcnt vmcnt(" #n ")" ::: "memory")
; #define PG8_BAR __builtin_amdgcn_s_barrier()
; template <class Epi, class Sched, bool ALIGN_EPI, bool I8 = false>
; __device__ __forceinline__ void gemm_phase(LAS unsigned char* lds, const Gemm g, const Sched& S, const Epi& E) {
;     ...
;     PG8_STAGE(PG8_SB(0, 0), cB, voffB); PG8_STAGE(PG8_SB(0, 1), cB + hstep, voffB); PG8_STAGE(PG8_SA(0, 0), cA, voffA); PG8_STAGE(PG8_SA(0, 1), cA + hstep, voffA);
;     if (wr == 1) PG8_BAR;
;     PG8_WAIT_V(2); PG8_BAR;
;     PG8_STAGE(PG8_SB(1, 0), cB + kstep, voffB); PG8_STAGE(PG8_SA(1, 0), cA + kstep, voffA); PG8_STAGE(PG8_SB(1, 1), cB + hstep + kstep, voffB);
;     PG8_WAIT_V(6); PG8_BAR;
.LBB0_402:
	s_add_u32 s12, s20, 0x1b200000
	s_addc_u32 s13, s21, 0
	s_lshl_b32 s14, s14, 5
	s_and_b32 s24, s14, 0x60
	s_mov_b64 s[14:15], 0x80
	s_add_i32 m0, s29, 0x18000
	v_lshl_add_u64 v[6:7], v[6:7], 0, s[14:15]
	s_lshl_b32 s7, s3, 13
	s_lshl_b32 s17, s24, 7
	global_load_lds_dwordx4 v[6:7], off
	v_lshl_add_u64 v[2:3], v[2:3], 0, s[14:15]
	s_add_i32 m0, s29, 0x1a000
	s_add_i32 s55, s29, 0x8000
	s_add_i32 s56, s29, 0xa000
	global_load_lds_dwordx4 v[2:3], off
	v_lshl_add_u64 v[0:1], v[0:1], 0, s[14:15]
	s_mov_b32 m0, s55
	s_add_u32 s18, s42, 0x80080
	global_load_lds_dwordx4 v[0:1], off
	v_lshl_add_u64 v[0:1], v[4:5], 0, s[14:15]
	s_mov_b32 m0, s56
	s_addc_u32 s19, s43, 0
	global_load_lds_dwordx4 v[0:1], off
	s_add_i32 m0, s29, 0x1c000
	v_lshl_add_u64 v[0:1], s[18:19], 0, v[130:131]
	global_load_lds_dwordx4 v[0:1], off
	v_lshl_add_u64 v[0:1], s[18:19], 0, v[134:135]
	s_add_i32 m0, s29, 0x1e000
	s_sext_i32_i8 s64, s2
	global_load_lds_dwordx4 v[0:1], off
	v_and_b32_e32 v0, 15, v217
	v_lshlrev_b32_e32 v1, 1, v11
	v_lshlrev_b32_e32 v2, 2, v217
	v_lshlrev_b32_e32 v3, 6, v217
	s_movk_i32 s2, 0x3c0
	v_lshl_or_b32 v144, s3, 6, v0
	v_lshl_or_b32 v0, v0, 6, v1
	v_and_b32_e32 v2, 32, v2
	v_and_or_b32 v1, v3, s2, v1
	v_bitop3_b32 v145, s17, v1, v2 bitop3:0xf6
	v_lshlrev_b32_e32 v1, 9, v217
	v_bitop3_b32 v0, v0, s7, v2 bitop3:0xde
	v_and_b32_e32 v1, 0x70000, v1
	v_lshlrev_b32_e32 v2, 12, v10
	v_or3_b32 v1, v8, v1, v2
	v_add_u32_e32 v136, v1, v9
	v_lshlrev_b32_e32 v1, 5, v12
	s_waitcnt vmcnt(8)
	s_barrier
	s_waitcnt vmcnt(6)
	s_cmpk_lt_u32 s16, 0x100
	v_and_b32_e32 v1, 0xf0000, v1
	s_cselect_b64 s[16:17], -1, 0
	v_or3_b32 v1, v8, v1, v2
	s_add_i32 s58, 0, 0x10000
	s_add_i32 s59, 0, 0x14000
	s_waitcnt lgkmcnt(0)
	s_ashr_i32 s57, s6, 31
	v_or_b32_e32 v146, s24, v11
	v_mov_b32_e32 v137, v131
	v_add_u32_e32 v138, v1, v9
	v_mov_b32_e32 v139, v131
	v_mov_b64_e32 v[140:141], 0x200
	v_mov_b64_e32 v[142:143], 0x1ff
	v_add_u32_e32 v147, s58, v145
	v_add_u32_e32 v148, s59, v145
	v_add_u32_e32 v149, 0, v0
	s_mov_b32 s60, 0x80000
	s_mov_b64 s[18:19], 0x90000
	s_mov_b32 s61, 0x90000
	s_mov_b64 s[24:25], 0xa0000
	s_mov_b32 s62, 0xa0000
	s_mov_b64 s[26:27], 0xb0000
	s_mov_b32 s63, 0xb0000
	s_barrier
	s_branch .LBB0_405

; #define PG8_STAGE(bufoff, gbase, voff) do { _Pragma("unroll") for (int _i = 0; _i < 2; ++_i) \
;         __builtin_amdgcn_global_load_lds((const unsigned*)((const char*)(gbase) + (voff)[_i]), (LAS unsigned*)(lds + (bufoff) + ldsw + _i * 8192), 16, 0, 0); } while (0)
; #define PG8_WAIT_V(n) asm volatile("s_waitcnt vmcnt(" #n ")" ::: "memory")
; #define PG8_BAR __builtin_amdgcn_s_barrier()
; template <class Epi, class Sched, bool ALIGN_EPI, bool I8 = false>
; __device__ __forceinline__ void gemm_phase(LAS unsigned char* lds, const Gemm g, const Sched& S, const Epi& E) {
;     ...
;     PG8_STAGE(PG8_SB(0, 0), cB, voffB); PG8_STAGE(PG8_SB(0, 1), cB + hstep, voffB); PG8_STAGE(PG8_SA(0, 0), cA, voffA); PG8_STAGE(PG8_SA(0, 1), cA + hstep, voffA);
;     if (wr == 1) PG8_BAR;
;     PG8_WAIT_V(2); PG8_BAR;
;     PG8_STAGE(PG8_SB(1, 0), cB + kstep, voffB); PG8_STAGE(PG8_SA(1, 0), cA + kstep, voffA); PG8_STAGE(PG8_SB(1, 1), cB + hstep + kstep, voffB);
;     PG8_WAIT_V(6); PG8_BAR;
.LBB0_533:
	s_add_u32 s10, s20, 0x37400000
	s_addc_u32 s11, s21, 0
	s_lshl_b32 s5, s12, 5
	s_mov_b64 s[12:13], 0x80
	s_add_i32 m0, s54, 0x18000
	v_lshl_add_u64 v[6:7], v[6:7], 0, s[12:13]
	s_lshl_b32 s4, s3, 13
	s_and_b32 s5, s5, 0x60
	global_load_lds_dwordx4 v[6:7], off
	v_lshl_add_u64 v[4:5], v[4:5], 0, s[12:13]
	s_add_i32 m0, s54, 0x1a000
	s_add_i32 s60, s54, 0x8000
	s_add_i32 s61, s54, 0xa000
	global_load_lds_dwordx4 v[4:5], off
	v_lshl_add_u64 v[0:1], v[0:1], 0, s[12:13]
	s_mov_b32 m0, s60
	s_add_u32 s16, s44, 0x80080
	global_load_lds_dwordx4 v[0:1], off
	v_lshl_add_u64 v[0:1], v[2:3], 0, s[12:13]
	s_mov_b32 m0, s61
	s_addc_u32 s17, s45, 0
	global_load_lds_dwordx4 v[0:1], off
	s_add_i32 m0, s54, 0x1c000
	v_lshl_add_u64 v[0:1], s[16:17], 0, v[130:131]
	global_load_lds_dwordx4 v[0:1], off
	v_lshl_add_u64 v[0:1], s[16:17], 0, v[134:135]
	s_add_i32 m0, s54, 0x1e000
	v_lshlrev_b32_e32 v2, 12, v156
	global_load_lds_dwordx4 v[0:1], off
	v_lshlrev_b32_e32 v1, 2, v154
	v_lshl_or_b32 v0, v154, 6, v155
	v_and_b32_e32 v1, 32, v1
	v_bitop3_b32 v0, v0, s4, v1 bitop3:0xde
	v_lshlrev_b32_e32 v1, 9, v217
	v_and_b32_e32 v1, 0x70000, v1
	v_or3_b32 v1, v158, v1, v2
	v_add_u32_e32 v138, v1, v159
	v_lshlrev_b32_e32 v1, 5, v160
	s_waitcnt vmcnt(8)
	s_barrier
	s_waitcnt vmcnt(6)
	s_cmpk_lt_u32 s14, 0x100
	v_and_b32_e32 v1, 0xf0000, v1
	v_lshl_or_b32 v166, s5, 7, v157
	s_cselect_b64 s[14:15], -1, 0
	v_or3_b32 v1, v158, v1, v2
	s_add_i32 s65, 0, 0x10000
	s_add_i32 s66, 0, 0x14000
	s_sext_i32_i16 s83, s2
	v_lshl_or_b32 v165, s3, 6, v154
	s_mov_b32 s62, 0x18000
	s_mov_b32 s63, 0x8000
	s_waitcnt lgkmcnt(0)
	s_ashr_i32 s64, s6, 31
	v_or_b32_e32 v167, s5, v152
	v_mov_b32_e32 v139, v137
	v_add_u32_e32 v140, v1, v159
	v_mov_b32_e32 v141, v137
	v_mov_b64_e32 v[142:143], 0x800
	v_mov_b64_e32 v[144:145], 0x7ff
	v_add_u32_e32 v168, s65, v166
	v_add_u32_e32 v169, s66, v166
	v_add_u32_e32 v170, 0, v0
	s_mov_b64 s[16:17], 0x40000
	s_mov_b32 s67, 0x40000
	s_mov_b64 s[18:19], 0x48000
	s_mov_b32 s68, 0x48000
	s_mov_b64 s[24:25], 0x50000
	s_mov_b32 s69, 0x50000
	s_mov_b64 s[26:27], 0x58000
	s_mov_b32 s70, 0x58000
	s_mov_b32 s71, 0x20000
	s_mov_b32 s72, 0x28000
	s_mov_b32 s73, 0x30000
	s_mov_b32 s74, 0x38000
	s_mov_b32 s75, 0x404000
	s_mov_b32 s76, 0x40c000
	s_mov_b32 s77, 0x414000
	s_mov_b32 s78, 0x41c000
	s_mov_b32 s79, 0x424000
	s_mov_b32 s80, 0x42c000
	s_mov_b32 s81, 0x434000
	s_mov_b32 s82, 0x43c000
	s_mov_b32 s28, 0xbfb8aa3b
	v_mov_b32_e32 v171, 0x3e38aa3b
	s_barrier
	s_branch .LBB0_536

; #define PG8_STAGE(bufoff, gbase, voff) do { _Pragma("unroll") for (int _i = 0; _i < 2; ++_i) \
;         __builtin_amdgcn_global_load_lds((const unsigned*)((const char*)(gbase) + (voff)[_i]), (LAS unsigned*)(lds + (bufoff) + ldsw + _i * 8192), 16, 0, 0); } while (0)
; #define PG8_WAIT_V(n) asm volatile("s_waitcnt vmcnt(" #n ")" ::: "memory")
; #define PG8_BAR __builtin_amdgcn_s_barrier()
; template <class Epi, class Sched, bool ALIGN_EPI, bool I8 = false>
; __device__ __forceinline__ void gemm_phase(LAS unsigned char* lds, const Gemm g, const Sched& S, const Epi& E) {
;     ...
;     PG8_STAGE(PG8_SB(0, 0), cB, voffB); PG8_STAGE(PG8_SB(0, 1), cB + hstep, voffB); PG8_STAGE(PG8_SA(0, 0), cA, voffA); PG8_STAGE(PG8_SA(0, 1), cA + hstep, voffA);
;     if (wr == 1) PG8_BAR;
;     PG8_WAIT_V(2); PG8_BAR;
;     PG8_STAGE(PG8_SB(1, 0), cB + kstep, voffB); PG8_STAGE(PG8_SA(1, 0), cA + kstep, voffA); PG8_STAGE(PG8_SB(1, 1), cB + hstep + kstep, voffB);
;     PG8_WAIT_V(6); PG8_BAR;
.LBB0_561:
	s_add_u32 s12, s20, 0x3fc00000
	s_addc_u32 s13, s21, 0
	s_lshl_b32 s5, s14, 5
	s_lshl_b32 s4, s24, 13
	s_and_b32 s5, s5, 0x60
	s_add_u32 s14, s20, 0x25200000
	s_addc_u32 s15, s21, 0
	s_add_u32 s16, s20, 0x39600000
	s_mov_b64 s[18:19], 0x80
	s_addc_u32 s17, s21, 0
	s_add_i32 m0, s67, 0x18000
	v_lshl_add_u64 v[6:7], v[6:7], 0, s[18:19]
	global_load_lds_dwordx4 v[6:7], off
	v_lshl_add_u64 v[4:5], v[4:5], 0, s[18:19]
	s_add_i32 m0, s67, 0x1a000
	s_add_i32 s73, s67, 0x8000
	s_add_i32 s74, s67, 0xa000
	global_load_lds_dwordx4 v[4:5], off
	v_lshl_add_u64 v[0:1], v[0:1], 0, s[18:19]
	s_mov_b32 m0, s73
	s_add_u32 s30, s56, 0x40080
	global_load_lds_dwordx4 v[0:1], off
	v_lshl_add_u64 v[0:1], v[2:3], 0, s[18:19]
	s_mov_b32 m0, s74
	s_addc_u32 s31, s57, 0
	global_load_lds_dwordx4 v[0:1], off
	s_add_i32 m0, s67, 0x1c000
	v_lshl_add_u64 v[0:1], s[30:31], 0, v[148:149]
	global_load_lds_dwordx4 v[0:1], off
	v_lshl_add_u64 v[0:1], s[30:31], 0, v[144:145]
	s_add_i32 m0, s67, 0x1e000
	v_or_b32_e32 v223, s5, v152
	global_load_lds_dwordx4 v[0:1], off
	v_lshlrev_b32_e32 v1, 2, v154
	v_lshl_or_b32 v0, v154, 6, v155
	v_and_b32_e32 v1, 32, v1
	v_lshlrev_b32_e32 v152, 2, v223
	s_sext_i32_i16 s60, s2
	v_bitop3_b32 v2, v0, s4, v1 bitop3:0xde
	s_cmpk_lt_u32 s3, 0x100
	v_lshl_add_u64 v[0:1], s[20:21], 0, v[152:153]
	s_mov_b64 s[2:3], 0xd000
	v_lshl_or_b32 v219, s24, 6, v154
	v_lshl_add_u64 v[154:155], v[0:1], 0, s[2:3]
	v_lshlrev_b32_e32 v0, 8, v217
	v_and_b32_e32 v0, 0x38000, v0
	v_lshlrev_b32_e32 v1, 11, v156
	v_or3_b32 v0, v158, v0, v1
	v_add_u32_e32 v156, v0, v159
	v_lshlrev_b32_e32 v0, 4, v160
	s_waitcnt vmcnt(8)
	s_barrier
	s_waitcnt vmcnt(6)
	v_and_b32_e32 v0, 0x78000, v0
	v_lshl_or_b32 v222, s5, 7, v157
	s_cselect_b64 s[24:25], -1, 0
	v_or3_b32 v0, v158, v0, v1
	s_add_i32 s79, 0, 0x10000
	s_add_i32 s80, 0, 0x14000
	s_mov_b32 s75, 0x18000
	s_mov_b32 s76, 0x8000
	v_or_b32_e32 v224, 0xfffff400, v223
	s_waitcnt lgkmcnt(0)
	s_ashr_i32 s77, s6, 31
	s_mov_b32 s78, 0x38000
	v_mov_b32_e32 v157, v153
	v_add_u32_e32 v158, v0, v159
	v_mov_b32_e32 v159, v153
	v_mov_b64_e32 v[160:161], 0x900
	v_mov_b64_e32 v[162:163], 0x8ff
	v_add_u32_e32 v225, s79, v222
	v_add_u32_e32 v226, s80, v222
	v_add_u32_e32 v227, 0, v2
	s_mov_b32 s26, 0x3c010204
	s_mov_b32 s28, 0xbfb8aa3b
	s_mov_b32 s81, 0x40000
	s_mov_b64 s[30:31], 0x48000
	s_mov_b32 s82, 0x48000
	s_mov_b64 s[34:35], 0x50000
	s_mov_b32 s83, 0x50000
	s_mov_b64 s[36:37], 0x58000
	s_mov_b32 s84, 0x58000
	s_mov_b32 s38, 0x3dd2d3e9
	s_mov_b32 s40, 0xc0135761
	s_mov_b32 s86, 0x20000
	s_mov_b32 s87, 0x28000
	s_mov_b32 s88, 0x30000
	s_mov_b32 s89, 0x404000
	s_mov_b32 s90, 0x40c000
	s_mov_b32 s91, 0x414000
	s_mov_b32 s92, 0x41c000
	s_mov_b32 s93, 0x424000
	s_mov_b32 s94, 0x42c000
	s_mov_b32 s95, 0x434000
	s_mov_b32 s96, 0x43c000
	s_mov_b32 s42, 0xbc3a1e78
	s_movk_i32 s97, 0x3000
	s_barrier
	s_branch .LBB0_564

; __device__ __forceinline__ void unpack8(const u32x4 w, float* v) { v[0] = bflo(w.x); v[1] = bfhi(w.x); v[2] = bflo(w.y); v[3] = bfhi(w.y); v[4] = bflo(w.z); v[5] = bfhi(w.z); v[6] = bflo(w.w); v[7] = bfhi(w.w); }
; __device__ __forceinline__ void conv_unit(const bf16_t* __restrict__ BB, const bf16_t* __restrict__ CC, const bf16_t* __restrict__ HB, const bf16_t* __restrict__ GB,
;                                           bf16_t* __restrict__ OB, const float* __restrict__ cw, int unit, int tid) {
;     const int cgp = tid & 127, sub = tid >> 7, ch = cgp * 8;
;     const int t0 = unit * 32 + sub * 8;
;     float w0[8], w1[8], w2[8];
; #pragma unroll
;     for (int e = 0; e < 8; ++e) { w0[e] = cw[ch + e]; w1[e] = cw[DH + ch + e]; w2[e] = cw[2 * DH + ch + e]; }
;     float p2[8], p1[8];
; #pragma unroll
;     for (int e = 0; e < 8; ++e) { p2[e] = 0.f; p1[e] = 0.f; }
;     const int tpos = t0 & (SEQ - 1);
;     if (tpos >= 2) { float a[8], b[8]; unpack8(*(const u32x4*)(CC + (size_t)(t0 - 2) * DH + ch), a); unpack8(*(const u32x4*)(HB + (size_t)(t0 - 2) * DH + ch), b);
; #pragma unroll
;         for (int e = 0; e < 8; ++e) p2[e] = a[e] * b[e]; }
;     if (tpos >= 1) { float a[8], b[8]; unpack8(*(const u32x4*)(CC + (size_t)(t0 - 1) * DH + ch), a); unpack8(*(const u32x4*)(HB + (size_t)(t0 - 1) * DH + ch), b);
; #pragma unroll
;         for (int e = 0; e < 8; ++e) p1[e] = a[e] * b[e]; }
.LBB0_659:
	s_and_b64 vcc, exec, s[8:9]
	s_cbranch_vccz .LBB0_670
	global_load_dwordx4 v[0:3], v[140:141], off offset:16
	global_load_dwordx4 v[12:15], v[140:141], off
	global_load_dwordx4 v[4:7], v[142:143], off offset:16
	global_load_dwordx4 v[20:23], v[142:143], off
	global_load_dwordx4 v[8:11], v[144:145], off offset:16
	global_load_dwordx4 v[16:19], v[144:145], off
	v_lshl_add_u32 v32, s6, 5, v161
	v_lshlrev_b32_e32 v56, 10, v32
	v_or_b32_e32 v57, v56, v160
	v_lshlrev_b32_e32 v57, 1, v57
	global_load_dwordx4 v[48:51], v57, s[40:41]
	global_load_dwordx4 v[52:55], v57, s[42:43]
	global_load_dwordx4 v[58:61], v57, s[38:39]
	global_load_dwordx4 v[62:65], v57, s[44:45]
	v_or_b32_e32 v108, 0x800, v57
	global_load_dwordx4 v[66:69], v108, s[40:41]
	global_load_dwordx4 v[70:73], v108, s[42:43]
	global_load_dwordx4 v[74:77], v108, s[38:39]
	global_load_dwordx4 v[78:81], v108, s[44:45]
	v_and_b32_e32 v24, 0x7f8, v32
	v_cmp_ne_u32_e32 vcc, 0, v24
	v_mov_b32_e32 v46, 0
	v_mov_b32_e32 v47, 0
	v_mov_b32_e32 v44, 0
	v_mov_b32_e32 v45, 0
	v_mov_b32_e32 v42, 0
	v_mov_b32_e32 v43, 0
	v_mov_b32_e32 v40, 0
	v_mov_b32_e32 v41, 0
	v_mov_b32_e32 v24, 0
	v_mov_b32_e32 v25, 0
	v_mov_b32_e32 v26, 0
	v_mov_b32_e32 v27, 0
	v_mov_b32_e32 v28, 0
	v_mov_b32_e32 v29, 0
	v_mov_b32_e32 v30, 0
	v_mov_b32_e32 v31, 0
	s_and_saveexec_b64 s[8:9], vcc
	s_cbranch_execz .LBB0_662
	v_add_u32_e32 v132, -2, v32
	v_lshlrev_b64 v[28:29], 11, v[132:133]
	v_add_u32_e32 v132, -1, v32
	v_lshl_add_u64 v[24:25], v[134:135], 0, v[28:29]
	v_lshl_add_u64 v[28:29], v[136:137], 0, v[28:29]
	v_lshlrev_b64 v[38:39], 11, v[132:133]
	global_load_dwordx4 v[24:27], v[24:25], off
	v_lshl_add_u64 v[34:35], v[134:135], 0, v[38:39]
	global_load_dwordx4 v[28:31], v[28:29], off
	v_lshl_add_u64 v[38:39], v[136:137], 0, v[38:39]
	global_load_dwordx4 v[34:37], v[34:35], off
	global_load_dwordx4 v[38:41], v[38:39], off
	s_waitcnt vmcnt(0)
	v_lshlrev_b32_e32 v42, 16, v24
	v_and_b32_e32 v43, 0xffff0000, v24
	v_lshlrev_b32_e32 v44, 16, v28
	v_and_b32_e32 v45, 0xffff0000, v28
	v_lshlrev_b32_e32 v46, 16, v25
	v_and_b32_e32 v47, 0xffff0000, v25
	v_lshlrev_b32_e32 v28, 16, v29
	v_and_b32_e32 v29, 0xffff0000, v29
	v_lshlrev_b32_e32 v236, 16, v26
	v_and_b32_e32 v237, 0xffff0000, v26
	v_lshlrev_b32_e32 v238, 16, v30
	v_and_b32_e32 v239, 0xffff0000, v30
	v_lshlrev_b32_e32 v240, 16, v27
	v_and_b32_e32 v241, 0xffff0000, v27
	v_lshlrev_b32_e32 v30, 16, v31
	v_and_b32_e32 v31, 0xffff0000, v31
	v_pk_mul_f32 v[24:25], v[42:43], v[44:45]
	v_pk_mul_f32 v[26:27], v[46:47], v[28:29]
	v_pk_mul_f32 v[28:29], v[236:237], v[238:239]
	v_lshlrev_b32_e32 v42, 16, v34
	v_and_b32_e32 v43, 0xffff0000, v34
	v_lshlrev_b32_e32 v34, 16, v35
	v_and_b32_e32 v35, 0xffff0000, v35
	v_lshlrev_b32_e32 v236, 16, v36
	v_and_b32_e32 v237, 0xffff0000, v36
	v_lshlrev_b32_e32 v36, 16, v37
	v_and_b32_e32 v37, 0xffff0000, v37
	v_pk_mul_f32 v[30:31], v[240:241], v[30:31]
	s_waitcnt vmcnt(0)
	v_lshlrev_b32_e32 v44, 16, v38
	v_and_b32_e32 v45, 0xffff0000, v38
	v_lshlrev_b32_e32 v38, 16, v39
	v_and_b32_e32 v39, 0xffff0000, v39
	v_lshlrev_b32_e32 v238, 16, v40
	v_and_b32_e32 v239, 0xffff0000, v40
	v_lshlrev_b32_e32 v40, 16, v41
	v_and_b32_e32 v41, 0xffff0000, v41
	v_pk_mul_f32 v[46:47], v[42:43], v[44:45]
	v_pk_mul_f32 v[44:45], v[34:35], v[38:39]
	v_pk_mul_f32 v[42:43], v[236:237], v[238:239]
	v_pk_mul_f32 v[40:41], v[36:37], v[40:41]

; #define LAS __attribute__((address_space(3)))
; #define MFMA32(a, b, c) __builtin_amdgcn_mfma_f32_32x32x16_bf16((a), (b), (c), 0, 0, 0)
; #define ATT_BAR() asm volatile("s_waitcnt lgkmcnt(0)\n\ts_barrier" ::: "memory")
; __device__ __forceinline__ void attn_item(const bf16_t* __restrict__ Q, const bf16_t* __restrict__ Kb, const bf16_t* __restrict__ VT, const bf16_t* __restrict__ GA, ...
;     ...
;     u32x4 tr[8];
; #pragma unroll
;     for (int i = 0; i < 8; ++i) tr[i] = *(const u32x4*)(tg + i * rstep);
;     bf16x8 qf[4];
;     { const bf16_t* qp = Q + (size_t)(tokq + r) * DH + h * 64 + 8 * hh;
; #pragma unroll
;       for (int d0 = 0; d0 < 4; ++d0) qf[d0] = *(const bf16x8*)(qp + d0 * 16); }
;     int buf = 0;
; #pragma unroll
;     for (int i = 0; i < 8; ++i) *(LAS u32x4*)(pl + stoff + 8 * i * ATP) = tr[i];
;     tg += (jmin + 1 <= 8) ? tstep : (size_t)0;
; #pragma unroll
;     for (int i = 0; i < 8; ++i) tr[i] = *(const u32x4*)(tg + i * rstep);
;     ATT_BAR();
;     f32x16 o0, o1, cinit;
; #pragma unroll
;     for (int i = 0; i < 16; ++i) { o0[i] = 0.f; o1[i] = 0.f; }
;     constexpr float ATT_THR = 8.f;
;     float mref = 0.f, lrun = 0.f;
;     const float cfar = btab[NREL - 1];
; #pragma unroll
;     for (int i = 0; i < 16; ++i) cinit[i] = cfar;
;     for (int j = jmin; j <= 8; ++j) {
;         const LAS unsigned char* kfp = pl + buf * ATT_WAVE_LDS + pr * ATP + 16 * hh;
;         const LAS unsigned char* vfp = pl + buf * ATT_WAVE_LDS + 64 * ATP + r * ATP + 16 * hh;
;         f32x16 s0, s1;
;         if (j <= 3) {
;             const bf16x8 k0 = *(const LAS bf16x8*)(kfp), k1 = *(const LAS bf16x8*)(kfp + 32 * ATP);
;             s0 = MFMA32(k0, qf[0], cinit); s1 = MFMA32(k1, qf[0], cinit);
;         } else {
;             const LAS float* bp = btab + (qloc + 64 * (8 - j) + 63 - 8 * hh);
; #pragma unroll
;             for (int i = 0; i < 16; ++i) {
;                 const int key = (i & 3) + 4 * ((i >> 2) & 1) + 16 * (i >> 3);
;                 s0[i] = bp[-key] - mref; s1[i] = bp[-key - 32] - mref;
;             }
;             const bf16x8 k0 = *(const LAS bf16x8*)(kfp), k1 = *(const LAS bf16x8*)(kfp + 32 * ATP);
;             s0 = MFMA32(k0, qf[0], s0); s1 = MFMA32(k1, qf[0], s1);
.LBB0_672:
	v_lshlrev_b32_e32 v132, 1, v138
	s_lshl_b32 s66, s66, 1
	v_lshl_add_u64 v[0:1], v[0:1], 0, v[132:133]
	s_mov_b32 s68, s66
	s_mov_b32 s69, s29
	v_lshl_add_u64 v[2:3], v[0:1], 0, s[68:69]
	global_load_dwordx4 v[34:37], v[0:1], off
	global_load_dwordx4 v[38:41], v[2:3], off
	v_lshl_add_u64 v[2:3], v[2:3], 0, s[68:69]
	v_lshl_add_u64 v[4:5], v[2:3], 0, s[68:69]
	global_load_dwordx4 v[42:45], v[2:3], off
	global_load_dwordx4 v[46:49], v[4:5], off
	v_lshl_add_u64 v[2:3], v[4:5], 0, s[68:69]
	v_lshl_add_u64 v[4:5], v[2:3], 0, s[68:69]
	global_load_dwordx4 v[50:53], v[2:3], off
	global_load_dwordx4 v[54:57], v[4:5], off
	v_lshl_add_u64 v[2:3], v[4:5], 0, s[68:69]
	v_lshl_add_u64 v[4:5], v[2:3], 0, s[68:69]
	global_load_dwordx4 v[58:61], v[2:3], off
	global_load_dwordx4 v[62:65], v[4:5], off
	v_add_u32_e32 v186, s65, v164
	s_lshl_b32 s7, s71, 6
	s_add_i32 s7, s7, s70
	v_and_b32_e32 v2, 64, v182
	s_or_b32 s65, s7, s78
	v_or_b32_e32 v226, s65, v131
	v_ashrrev_i32_e32 v227, 31, v226
	v_lshlrev_b64 v[226:227], 11, v[226:227]
	v_lshl_add_u64 v[226:227], s[24:25], 0, v[226:227]
	v_lshl_add_u64 v[226:227], s[8:9], 1, v[226:227]
	v_lshlrev_b32_e32 v228, 1, v130
	v_mov_b32_e32 v229, 0
	v_lshl_add_u64 v[226:227], v[226:227], 0, v[228:229]
	global_load_dwordx4 v[82:85], v[226:227], off
	global_load_dwordx4 v[86:89], v[226:227], off offset:32
	global_load_dwordx4 v[90:93], v[226:227], off offset:64
	global_load_dwordx4 v[94:97], v[226:227], off offset:96
	v_xor_b32_e32 v184, 32, v182
	v_mov_b32_e32 v33, 0
	v_mov_b32_e32 v32, 0
	v_mov_b32_e32 v31, 0
	v_mov_b32_e32 v30, 0
	v_mov_b32_e32 v29, 0
	v_mov_b32_e32 v28, 0
	v_mov_b32_e32 v27, 0
	v_mov_b32_e32 v26, 0
	v_mov_b32_e32 v25, 0
	v_mov_b32_e32 v24, 0
	v_mov_b32_e32 v23, 0
	v_mov_b32_e32 v22, 0
	v_mov_b32_e32 v21, 0
	v_mov_b32_e32 v20, 0
	v_mov_b32_e32 v19, 0
	v_mov_b32_e32 v18, 0
	v_mov_b32_e32 v17, 0
	v_mov_b32_e32 v16, 0
	v_mov_b32_e32 v15, 0
	v_mov_b32_e32 v14, 0
	v_mov_b32_e32 v13, 0
	v_mov_b32_e32 v12, 0
	v_mov_b32_e32 v11, 0
	v_mov_b32_e32 v10, 0
	v_mov_b32_e32 v9, 0
	v_mov_b32_e32 v8, 0
	v_mov_b32_e32 v7, 0
	v_mov_b32_e32 v6, 0
	v_mov_b32_e32 v5, 0
	v_add_u32_e32 v185, 64, v2
	s_cmp_gt_i32 s84, 8
	v_mov_b32_e32 v4, 0
	v_mov_b32_e32 v3, 0
	v_mov_b32_e32 v2, 0
	v_mov_b32_e32 v187, 0
	s_waitcnt vmcnt(0)
	ds_write_b128 v186, v[34:37]
	ds_write_b128 v186, v[38:41] offset:1152
	ds_write_b128 v186, v[42:45] offset:2304
	ds_write_b128 v186, v[46:49] offset:3456
	ds_write_b128 v186, v[50:53] offset:4608
	ds_write_b128 v186, v[54:57] offset:5760
	ds_write_b128 v186, v[58:61] offset:6912
	ds_write_b128 v186, v[62:65] offset:8064
	s_waitcnt lgkmcnt(0)
	s_barrier
	s_cbranch_scc1 .LBB0_641
	s_cmp_lt_i32 s84, 8
	v_or_b32_e32 v2, s65, v131
	s_cselect_b64 s[70:71], -1, 0
	v_ashrrev_i32_e32 v3, 31, v2
	s_and_b64 s[72:73], s[70:71], exec
	v_lshlrev_b64 v[2:3], 11, v[2:3]
	s_cselect_b32 s7, s64, 0
	v_lshl_add_u64 v[2:3], s[24:25], 0, v[2:3]
	s_lshl_b32 s28, s7, 1
	v_lshl_add_u64 v[2:3], s[8:9], 1, v[2:3]
	v_lshlrev_b32_e32 v132, 1, v130
	v_lshl_add_u64 v[80:81], v[0:1], 0, s[28:29]
	v_lshl_add_u64 v[2:3], v[2:3], 0, v[132:133]
	v_lshl_add_u64 v[0:1], v[80:81], 0, s[68:69]
	v_lshl_add_u64 v[2:3], v[0:1], 0, s[68:69]
	global_load_dwordx4 v[48:51], v[80:81], off
	global_load_dwordx4 v[52:55], v[0:1], off
	global_load_dwordx4 v[56:59], v[2:3], off
	v_lshl_add_u64 v[0:1], v[2:3], 0, s[68:69]
	v_lshl_add_u64 v[2:3], v[0:1], 0, s[68:69]
	global_load_dwordx4 v[60:63], v[0:1], off
	global_load_dwordx4 v[64:67], v[2:3], off
	v_lshl_add_u64 v[0:1], v[2:3], 0, s[68:69]
	v_lshl_add_u64 v[2:3], v[0:1], 0, s[68:69]
	global_load_dwordx4 v[68:71], v[0:1], off
	global_load_dwordx4 v[72:75], v[2:3], off
	v_lshl_add_u64 v[0:1], v[2:3], 0, s[68:69]
	global_load_dwordx4 v[76:79], v[0:1], off
	v_mov_b32_e32 v0, s75
	ds_read_b32 v0, v0 offset:1276
	s_cmp_lt_i32 s84, 4
	s_mov_b64 s[72:73], -1
	s_cbranch_scc1 .LBB0_675
	v_lshl_or_b32 v1, s84, 6, v130
	v_sub_u32_e32 v1, v173, v1
	v_lshl_add_u32 v1, v1, 2, s75
	v_add_u32_e32 v16, 0x860, v1
	ds_read2_b32 v[40:41], v16 offset1:1
	v_add_u32_e32 v16, 0x8b8, v1
	v_add_u32_e32 v2, 0x8f8, v1
	ds_read2_b32 v[26:27], v16 offset1:1
	v_add_u32_e32 v16, 0x838, v1
	ds_read2_b32 v[2:3], v2 offset1:1
	ds_read2_b32 v[42:43], v16 offset1:1
	v_add_u32_e32 v16, 0x8b0, v1
	ds_read2_b32 v[28:29], v16 offset1:1
	v_add_u32_e32 v16, 0x830, v1
	ds_read2_b32 v[44:45], v16 offset1:1
	v_add_u32_e32 v16, 0x8a8, v1
	ds_read2_b32 v[30:31], v16 offset1:1
	v_add_u32_e32 v16, 0x828, v1
	v_add_u32_e32 v4, 0x878, v1
	v_add_u32_e32 v6, 0x8f0, v1
	v_add_u32_e32 v8, 0x870, v1
	v_add_u32_e32 v10, 0x8e8, v1
	v_add_u32_e32 v12, 0x868, v1
	v_add_u32_e32 v14, 0x8e0, v1
	ds_read2_b32 v[46:47], v16 offset1:1
	v_add_u32_e32 v16, 0x8a0, v1
	v_add_u32_e32 v1, 0x820, v1
	ds_read2_b32 v[4:5], v4 offset1:1
	ds_read2_b32 v[8:9], v8 offset1:1
	ds_read2_b32 v[12:13], v12 offset1:1
	ds_read2_b32 v[6:7], v6 offset1:1
	ds_read2_b32 v[10:11], v10 offset1:1
	ds_read2_b32 v[14:15], v14 offset1:1
	ds_read2_b32 v[32:33], v16 offset1:1
	s_waitcnt lgkmcnt(12)
	v_mov_b32_e32 v16, v3
	v_mov_b32_e32 v17, v2
	ds_read2_b32 v[2:3], v1 offset1:1
	s_waitcnt lgkmcnt(4)
	v_mov_b32_e32 v18, v7
	v_mov_b32_e32 v19, v6
	v_mov_b32_e32 v24, v27
	v_mov_b32_e32 v25, v26
	v_mov_b32_e32 v26, v29
	v_mov_b32_e32 v27, v28
	v_mov_b32_e32 v28, v31
	v_mov_b32_e32 v29, v30
	s_waitcnt lgkmcnt(1)
	v_mov_b32_e32 v30, v33
	v_mov_b32_e32 v31, v32
	v_mov_b32_e32 v32, v5
	v_mov_b32_e32 v33, v4
	v_mov_b32_e32 v34, v9
	v_mov_b32_e32 v35, v8
	v_mov_b32_e32 v38, v41
	v_mov_b32_e32 v39, v40
	v_mov_b32_e32 v40, v43
	v_mov_b32_e32 v41, v42
	v_mov_b32_e32 v42, v45
	v_mov_b32_e32 v43, v44
	v_mov_b32_e32 v44, v47
	v_mov_b32_e32 v45, v46
	s_waitcnt lgkmcnt(0)
	v_mov_b32_e32 v46, v3
	v_mov_b32_e32 v47, v2
	ds_read_b128 v[2:5], v183
	ds_read_b128 v[6:9], v183 offset:4608
	v_mov_b32_e32 v20, v11
	v_mov_b32_e32 v21, v10
	v_mov_b32_e32 v22, v15
	v_mov_b32_e32 v23, v14
	v_mov_b32_e32 v36, v13
	v_mov_b32_e32 v37, v12
	s_waitcnt vmcnt(11) lgkmcnt(1)
	v_mfma_f32_32x32x16_bf16 v[16:31], v[2:5], v[82:85], v[16:31]
	s_mov_b64 s[72:73], 0
	s_waitcnt lgkmcnt(0)
	v_mfma_f32_32x32x16_bf16 v[32:47], v[6:9], v[82:85], v[32:47]
